# single accumulator zeroing per GEMM unit; in-proj first K-iteration after an epilogue waits only for pre-store loads (vmcnt 24 at ph4, vmcnt 10 at ph6)
# speedup vs baseline: 1.0203x; 1.0029x over previous
.LBB0_169:
	s_ashr_i32 s15, s14, 31
	v_cmp_lt_i64_e64 s[24:25], s[16:17], 64
	s_lshl_b64 s[16:17], s[14:15], 19
	s_add_u32 s16, s3, s16
	s_addc_u32 s17, s28, s17
	s_ashr_i32 s13, s12, 31
	s_lshl_b64 s[18:19], s[12:13], 19
	s_add_u32 s18, s29, s18
	s_addc_u32 s19, s30, s19
	s_andn2_b64 vcc, exec, s[6:7]
	s_cbranch_vccnz .Lzk_1
	s_and_b64 s[24:25], s[24:25], exec
	s_cselect_b32 s13, s17, s21
	s_cselect_b32 s15, s16, s20
	s_cselect_b32 s58, s19, s23
	s_cselect_b32 s59, s18, s22
	s_add_u32 s20, s20, 0x40080
	s_addc_u32 s21, s21, 0
	s_add_u32 s60, s22, 0x100
	v_mov_b32_e32 v0, 0
	s_addc_u32 s61, s23, 0
	s_mov_b32 s22, 0
	v_mov_b32_e32 v1, v0
	v_mov_b32_e32 v2, v0
	v_mov_b32_e32 v3, v0
	v_mov_b32_e32 v4, v0
	v_mov_b32_e32 v5, v0
	v_mov_b32_e32 v6, v0
	v_mov_b32_e32 v7, v0
	v_mov_b32_e32 v20, v0
	v_mov_b32_e32 v21, v0
	v_mov_b32_e32 v22, v0
	v_mov_b32_e32 v23, v0
	v_mov_b32_e32 v16, v0
	v_mov_b32_e32 v17, v0
	v_mov_b32_e32 v18, v0
	v_mov_b32_e32 v19, v0
	v_mov_b32_e32 v36, v0
	v_mov_b32_e32 v37, v0
	v_mov_b32_e32 v38, v0
	v_mov_b32_e32 v39, v0
	v_mov_b32_e32 v32, v0
	v_mov_b32_e32 v33, v0
	v_mov_b32_e32 v34, v0
	v_mov_b32_e32 v35, v0
	v_mov_b32_e32 v52, v0
	v_mov_b32_e32 v53, v0
	v_mov_b32_e32 v54, v0
	v_mov_b32_e32 v55, v0
	v_mov_b32_e32 v48, v0
	v_mov_b32_e32 v49, v0
	v_mov_b32_e32 v50, v0
	v_mov_b32_e32 v51, v0
	v_mov_b32_e32 v12, v0
	v_mov_b32_e32 v13, v0
	v_mov_b32_e32 v14, v0
	v_mov_b32_e32 v15, v0
	v_mov_b32_e32 v8, v0
	v_mov_b32_e32 v9, v0
	v_mov_b32_e32 v10, v0
	v_mov_b32_e32 v11, v0
	v_mov_b32_e32 v28, v0
	v_mov_b32_e32 v29, v0
	v_mov_b32_e32 v30, v0
	v_mov_b32_e32 v31, v0
	v_mov_b32_e32 v24, v0
	v_mov_b32_e32 v25, v0
	v_mov_b32_e32 v26, v0
	v_mov_b32_e32 v27, v0
	v_mov_b32_e32 v44, v0
	v_mov_b32_e32 v45, v0
	v_mov_b32_e32 v46, v0
	v_mov_b32_e32 v47, v0
	v_mov_b32_e32 v40, v0
	v_mov_b32_e32 v41, v0
	v_mov_b32_e32 v42, v0
	v_mov_b32_e32 v43, v0
	v_mov_b32_e32 v60, v0
	v_mov_b32_e32 v61, v0
	v_mov_b32_e32 v62, v0
	v_mov_b32_e32 v63, v0
	v_mov_b32_e32 v56, v0
	v_mov_b32_e32 v57, v0
	v_mov_b32_e32 v58, v0
	v_mov_b32_e32 v59, v0
	v_mov_b32_e32 v68, v0
	v_mov_b32_e32 v69, v0
	v_mov_b32_e32 v70, v0
	v_mov_b32_e32 v71, v0
	v_mov_b32_e32 v64, v0
	v_mov_b32_e32 v65, v0
	v_mov_b32_e32 v66, v0
	v_mov_b32_e32 v67, v0
	v_mov_b32_e32 v84, v0
	v_mov_b32_e32 v85, v0
	v_mov_b32_e32 v86, v0
	v_mov_b32_e32 v87, v0
	v_mov_b32_e32 v80, v0
	v_mov_b32_e32 v81, v0
	v_mov_b32_e32 v82, v0
	v_mov_b32_e32 v83, v0
	v_mov_b32_e32 v100, v0
	v_mov_b32_e32 v101, v0
	v_mov_b32_e32 v102, v0
	v_mov_b32_e32 v103, v0
	v_mov_b32_e32 v96, v0
	v_mov_b32_e32 v97, v0
	v_mov_b32_e32 v98, v0
	v_mov_b32_e32 v99, v0
	v_mov_b32_e32 v116, v0
	v_mov_b32_e32 v117, v0
	v_mov_b32_e32 v118, v0
	v_mov_b32_e32 v119, v0
	v_mov_b32_e32 v112, v0
	v_mov_b32_e32 v113, v0
	v_mov_b32_e32 v114, v0
	v_mov_b32_e32 v115, v0
	v_mov_b32_e32 v76, v0
	v_mov_b32_e32 v77, v0
	v_mov_b32_e32 v78, v0
	v_mov_b32_e32 v79, v0
	v_mov_b32_e32 v72, v0
	v_mov_b32_e32 v73, v0
	v_mov_b32_e32 v74, v0
	v_mov_b32_e32 v75, v0
	v_mov_b32_e32 v92, v0
	v_mov_b32_e32 v93, v0
	v_mov_b32_e32 v94, v0
	v_mov_b32_e32 v95, v0
	v_mov_b32_e32 v88, v0
	v_mov_b32_e32 v89, v0
	v_mov_b32_e32 v90, v0
	v_mov_b32_e32 v91, v0
	v_mov_b32_e32 v108, v0
	v_mov_b32_e32 v109, v0
	v_mov_b32_e32 v110, v0
	v_mov_b32_e32 v111, v0
	v_mov_b32_e32 v104, v0
	v_mov_b32_e32 v105, v0
	v_mov_b32_e32 v106, v0
	v_mov_b32_e32 v107, v0
	v_mov_b32_e32 v124, v0
	v_mov_b32_e32 v125, v0
	v_mov_b32_e32 v126, v0
	v_mov_b32_e32 v127, v0
	v_mov_b32_e32 v120, v0
	v_mov_b32_e32 v121, v0
	v_mov_b32_e32 v122, v0
	v_mov_b32_e32 v123, v0

.Lzk_1:
	v_mov_b32_e32 v123, 0
	v_mov_b32_e32 v122, v123
	v_mov_b32_e32 v121, v123
	v_mov_b32_e32 v120, v123
	v_mov_b32_e32 v127, v123
	v_mov_b32_e32 v126, v123
	v_mov_b32_e32 v125, v123
	v_mov_b32_e32 v124, v123
	v_mov_b32_e32 v107, v123
	v_mov_b32_e32 v106, v123
	v_mov_b32_e32 v105, v123
	v_mov_b32_e32 v104, v123
	v_mov_b32_e32 v111, v123
	v_mov_b32_e32 v110, v123
	v_mov_b32_e32 v109, v123
	v_mov_b32_e32 v108, v123
	v_mov_b32_e32 v91, v123
	v_mov_b32_e32 v90, v123
	v_mov_b32_e32 v89, v123
	v_mov_b32_e32 v88, v123
	v_mov_b32_e32 v95, v123
	v_mov_b32_e32 v94, v123
	v_mov_b32_e32 v93, v123
	v_mov_b32_e32 v92, v123
	v_mov_b32_e32 v75, v123
	v_mov_b32_e32 v74, v123
	v_mov_b32_e32 v73, v123
	v_mov_b32_e32 v72, v123
	v_mov_b32_e32 v79, v123
	v_mov_b32_e32 v78, v123
	v_mov_b32_e32 v77, v123
	v_mov_b32_e32 v76, v123
	v_mov_b32_e32 v115, v123
	v_mov_b32_e32 v114, v123
	v_mov_b32_e32 v113, v123
	v_mov_b32_e32 v112, v123
	v_mov_b32_e32 v119, v123
	v_mov_b32_e32 v118, v123
	v_mov_b32_e32 v117, v123
	v_mov_b32_e32 v116, v123
	v_mov_b32_e32 v99, v123
	v_mov_b32_e32 v98, v123
	v_mov_b32_e32 v97, v123
	v_mov_b32_e32 v96, v123
	v_mov_b32_e32 v103, v123
	v_mov_b32_e32 v102, v123
	v_mov_b32_e32 v101, v123
	v_mov_b32_e32 v100, v123
	v_mov_b32_e32 v83, v123
	v_mov_b32_e32 v82, v123
	v_mov_b32_e32 v81, v123
	v_mov_b32_e32 v80, v123
	v_mov_b32_e32 v87, v123
	v_mov_b32_e32 v86, v123
	v_mov_b32_e32 v85, v123
	v_mov_b32_e32 v84, v123
	v_mov_b32_e32 v67, v123
	v_mov_b32_e32 v66, v123
	v_mov_b32_e32 v65, v123
	v_mov_b32_e32 v64, v123
	v_mov_b32_e32 v71, v123
	v_mov_b32_e32 v70, v123
	v_mov_b32_e32 v69, v123
	v_mov_b32_e32 v68, v123
	v_mov_b32_e32 v59, v123
	v_mov_b32_e32 v58, v123
	v_mov_b32_e32 v57, v123
	v_mov_b32_e32 v56, v123
	v_mov_b32_e32 v63, v123
	v_mov_b32_e32 v62, v123
	v_mov_b32_e32 v61, v123
	v_mov_b32_e32 v60, v123
	v_mov_b32_e32 v43, v123
	v_mov_b32_e32 v42, v123
	v_mov_b32_e32 v41, v123
	v_mov_b32_e32 v40, v123
	v_mov_b32_e32 v47, v123
	v_mov_b32_e32 v46, v123
	v_mov_b32_e32 v45, v123
	v_mov_b32_e32 v44, v123
	v_mov_b32_e32 v27, v123
	v_mov_b32_e32 v26, v123
	v_mov_b32_e32 v25, v123
	v_mov_b32_e32 v24, v123
	v_mov_b32_e32 v31, v123
	v_mov_b32_e32 v30, v123
	v_mov_b32_e32 v29, v123
	v_mov_b32_e32 v28, v123
	v_mov_b32_e32 v11, v123
	v_mov_b32_e32 v10, v123
	v_mov_b32_e32 v9, v123
	v_mov_b32_e32 v8, v123
	v_mov_b32_e32 v15, v123
	v_mov_b32_e32 v14, v123
	v_mov_b32_e32 v13, v123
	v_mov_b32_e32 v12, v123
	v_mov_b32_e32 v51, v123
	v_mov_b32_e32 v50, v123
	v_mov_b32_e32 v49, v123
	v_mov_b32_e32 v48, v123
	v_mov_b32_e32 v55, v123
	v_mov_b32_e32 v54, v123
	v_mov_b32_e32 v53, v123
	v_mov_b32_e32 v52, v123
	v_mov_b32_e32 v35, v123
	v_mov_b32_e32 v34, v123
	v_mov_b32_e32 v33, v123
	v_mov_b32_e32 v32, v123
	v_mov_b32_e32 v39, v123
	v_mov_b32_e32 v38, v123
	v_mov_b32_e32 v37, v123
	v_mov_b32_e32 v36, v123
	v_mov_b32_e32 v19, v123
	v_mov_b32_e32 v18, v123
	v_mov_b32_e32 v17, v123
	v_mov_b32_e32 v16, v123
	v_mov_b32_e32 v23, v123
	v_mov_b32_e32 v22, v123
	v_mov_b32_e32 v21, v123
	v_mov_b32_e32 v20, v123
	v_mov_b32_e32 v7, v123
	v_mov_b32_e32 v6, v123
	v_mov_b32_e32 v5, v123
	v_mov_b32_e32 v4, v123
	v_mov_b32_e32 v3, v123
	v_mov_b32_e32 v2, v123
	v_mov_b32_e32 v1, v123
	v_mov_b32_e32 v0, v123
	s_branch .LBB0_162

.LBB0_233:
	s_and_b32 s6, s4, 3
	s_ashr_i32 s4, s0, 31
	v_bfe_u32 v18, v8, 4, 2
	s_lshr_b32 s4, s4, 26
	v_and_b32_e32 v19, 15, v8
	s_add_i32 s4, s0, s4
	v_lshlrev_b32_e32 v1, 4, v18
	v_lshlrev_b32_e32 v20, 2, v8
	s_ashr_i32 s27, s4, 6
	v_lshl_or_b32 v1, v19, 6, v1
	s_lshl_b32 s7, s1, 13
	v_and_b32_e32 v20, 32, v20
	s_lshl_b32 s4, s6, 12
	v_readlane_b32 s14, v253, 57
	v_bitop3_b32 v21, v1, s7, v20 bitop3:0xde
	v_bitop3_b32 v1, v1, s4, v20 bitop3:0xde
	s_mov_b64 s[4:5], 0x80
	v_mov_b32_e32 v137, v0
	v_readlane_b32 s15, v253, 58
	s_add_i32 m0, s23, 0x18000
	v_lshl_add_u64 v[2:3], v[2:3], 0, s[4:5]
	v_lshl_add_u64 v[14:15], s[14:15], 0, v[136:137]
	v_mov_b32_e32 v133, v0
	s_waitcnt vmcnt(4)
	s_barrier
	global_load_lds_dwordx4 v[2:3], off
	v_lshl_add_u64 v[2:3], v[4:5], 0, s[4:5]
	s_add_i32 m0, s23, 0x1a000
	s_add_i32 s28, s23, 0x8000
	v_lshl_add_u64 v[16:17], s[14:15], 0, v[132:133]
	global_load_lds_dwordx4 v[2:3], off
	v_lshl_add_u64 v[2:3], v[14:15], 0, s[4:5]
	s_mov_b32 m0, s28
	s_add_i32 s29, s23, 0xa000
	global_load_lds_dwordx4 v[2:3], off
	v_lshl_add_u64 v[2:3], v[16:17], 0, s[4:5]
	s_add_u32 s4, s16, 0x40080
	s_mov_b32 m0, s29
	s_addc_u32 s5, s17, 0
	global_load_lds_dwordx4 v[2:3], off
	s_add_i32 m0, s23, 0x1c000
	v_lshl_add_u64 v[2:3], s[4:5], 0, v[134:135]
	global_load_lds_dwordx4 v[2:3], off
	v_lshl_add_u64 v[2:3], s[4:5], 0, v[130:131]
	s_add_i32 m0, s23, 0x1e000
	v_lshrrev_b32_e32 v13, 4, v8
	global_load_lds_dwordx4 v[2:3], off
	v_and_b32_e32 v2, 7, v8
	v_bitop3_b32 v4, v13, v2, 3 bitop3:0x6c
	v_lshrrev_b32_e32 v5, 3, v8
	v_lshlrev_b32_e32 v3, 7, v19
	v_lshlrev_b32_e32 v4, 4, v4
	v_bitop3_b32 v5, v5, v8, 7 bitop3:0x28
	v_readlane_b32 s8, v252, 13
	v_or_b32_e32 v13, v4, v3
	v_bfe_u32 v16, v8, 3, 3
	v_lshlrev_b32_e32 v8, 4, v5
	v_bitop3_b32 v3, v4, 64, v3 bitop3:0x36
	v_lshlrev_b32_e32 v4, 8, v18
	v_mov_b32_e32 v5, v0
	v_readlane_b32 s9, v252, 14
	v_lshlrev_b32_e32 v14, 4, v19
	v_mov_b32_e32 v15, v0
	v_lshl_add_u64 v[4:5], s[8:9], 0, v[4:5]
	v_lshl_or_b32 v150, s1, 6, v16
	s_lshl_b32 s1, s1, 2
	v_lshl_add_u64 v[138:139], v[4:5], 0, v[14:15]
	v_lshlrev_b32_e32 v5, 14, v11
	s_or_b32 s30, s1, s6
	v_and_b32_e32 v5, 0xffff8000, v5
	s_lshl_b32 s4, s6, 11
	s_lshl_b32 s5, s6, 6
	s_addk_i32 s30, 0xff00
	v_lshl_add_u32 v5, v10, 11, v5
	v_and_b32_e32 v10, 1, v11
	s_cmp_gt_i32 s0, 63
	v_lshl_or_b32 v5, v10, 6, v5
	s_cselect_b64 s[0:1], -1, 0
	s_add_i32 s6, s7, 0
	v_lshl_add_u32 v140, v12, 1, v5
	v_lshlrev_b32_e32 v5, 14, v6
	s_add_i32 s4, s6, s4
	v_and_b32_e32 v5, 0xffff8000, v5
	s_waitcnt vmcnt(6)
	s_add_i32 s4, s4, 0x20000
	v_lshl_add_u32 v5, v7, 11, v5
	v_and_b32_e32 v6, 1, v6
	v_lshlrev_b32_e32 v2, 3, v2
	v_lshl_add_u32 v4, v16, 7, s4
	v_lshl_or_b32 v5, v6, 6, v5
	s_lshl_b32 s36, s5, 1
	v_add_u32_e32 v152, s4, v13
	v_add_u32_e32 v153, s4, v3
	v_readlane_b32 s4, v253, 55
	s_add_i32 s31, s27, -2
	v_mov_b32_e32 v141, v0
	v_lshl_add_u32 v142, v9, 1, v5
	v_mov_b32_e32 v143, v0
	s_mov_b32 s34, 0
	v_add_u32_e32 v151, 0, v21
	s_mov_b64 s[46:47], s[36:37]
	v_lshlrev_b32_e32 v148, 1, v2
	v_add_u32_e32 v154, v4, v8
	v_readlane_b32 s35, v253, 52
	s_mov_b32 s36, s4
	s_barrier
	v_readlane_b32 s5, v253, 56
	s_mov_b32 s100, 0
	s_branch .LBB0_235

.LBB0_237:
	s_ashr_i32 s9, s8, 31
	s_lshl_b64 s[10:11], s[8:9], 19
	s_add_u32 s10, s49, s10
	s_addc_u32 s11, s52, s11
	s_ashr_i32 s7, s6, 31
	s_lshl_b64 s[12:13], s[6:7], 19
	s_add_u32 s12, s20, s12
	s_addc_u32 s13, s21, s13
	s_andn2_b64 vcc, exec, s[0:1]
	s_cbranch_vccnz .Lzk_2
	v_mov_b64_e32 v[2:3], 0xc00
	v_cmp_lt_i64_e32 vcc, s[18:19], v[2:3]
	s_and_b64 s[18:19], vcc, exec
	s_cselect_b32 s7, s11, s15
	s_cselect_b32 s9, s10, s14
	s_cselect_b32 s37, s13, s17
	s_cselect_b32 s38, s12, s16
	s_add_u32 s14, s14, 0x40080
	s_addc_u32 s15, s15, 0
	s_add_u32 s39, s16, 0x100
	v_mov_b32_e32 v2, 0
	v_mov_b32_e32 v218, 0xff800000
	v_mov_b32_e32 v155, 0xffffff80
	s_addc_u32 s40, s17, 0
	s_mov_b32 s16, 0
	v_mov_b32_e32 v3, v2
	v_mov_b32_e32 v4, v2
	v_mov_b32_e32 v5, v2
	v_mov_b32_e32 v6, v2
	v_mov_b32_e32 v7, v2
	v_mov_b32_e32 v8, v2
	v_mov_b32_e32 v9, v2
	v_mov_b32_e32 v22, v2
	v_mov_b32_e32 v23, v2
	v_mov_b32_e32 v24, v2
	v_mov_b32_e32 v25, v2
	v_mov_b32_e32 v18, v2
	v_mov_b32_e32 v19, v2
	v_mov_b32_e32 v20, v2
	v_mov_b32_e32 v21, v2
	v_mov_b32_e32 v38, v2
	v_mov_b32_e32 v39, v2
	v_mov_b32_e32 v40, v2
	v_mov_b32_e32 v41, v2
	v_mov_b32_e32 v34, v2
	v_mov_b32_e32 v35, v2
	v_mov_b32_e32 v36, v2
	v_mov_b32_e32 v37, v2
	v_mov_b32_e32 v54, v2
	v_mov_b32_e32 v55, v2
	v_mov_b32_e32 v56, v2
	v_mov_b32_e32 v57, v2
	v_mov_b32_e32 v50, v2
	v_mov_b32_e32 v51, v2
	v_mov_b32_e32 v52, v2
	v_mov_b32_e32 v53, v2
	v_mov_b32_e32 v14, v2
	v_mov_b32_e32 v15, v2
	v_mov_b32_e32 v16, v2
	v_mov_b32_e32 v17, v2
	v_mov_b32_e32 v10, v2
	v_mov_b32_e32 v11, v2
	v_mov_b32_e32 v12, v2
	v_mov_b32_e32 v13, v2
	v_mov_b32_e32 v30, v2
	v_mov_b32_e32 v31, v2
	v_mov_b32_e32 v32, v2
	v_mov_b32_e32 v33, v2
	v_mov_b32_e32 v26, v2
	v_mov_b32_e32 v27, v2
	v_mov_b32_e32 v28, v2
	v_mov_b32_e32 v29, v2
	v_mov_b32_e32 v46, v2
	v_mov_b32_e32 v47, v2
	v_mov_b32_e32 v48, v2
	v_mov_b32_e32 v49, v2
	v_mov_b32_e32 v42, v2
	v_mov_b32_e32 v43, v2
	v_mov_b32_e32 v44, v2
	v_mov_b32_e32 v45, v2
	v_mov_b32_e32 v62, v2
	v_mov_b32_e32 v63, v2
	v_mov_b32_e32 v64, v2
	v_mov_b32_e32 v65, v2
	v_mov_b32_e32 v58, v2
	v_mov_b32_e32 v59, v2
	v_mov_b32_e32 v60, v2
	v_mov_b32_e32 v61, v2
	v_mov_b32_e32 v70, v2
	v_mov_b32_e32 v71, v2
	v_mov_b32_e32 v72, v2
	v_mov_b32_e32 v73, v2
	v_mov_b32_e32 v66, v2
	v_mov_b32_e32 v67, v2
	v_mov_b32_e32 v68, v2
	v_mov_b32_e32 v69, v2
	v_mov_b32_e32 v86, v2
	v_mov_b32_e32 v87, v2
	v_mov_b32_e32 v88, v2
	v_mov_b32_e32 v89, v2
	v_mov_b32_e32 v82, v2
	v_mov_b32_e32 v83, v2
	v_mov_b32_e32 v84, v2
	v_mov_b32_e32 v85, v2
	v_mov_b32_e32 v102, v2
	v_mov_b32_e32 v103, v2
	v_mov_b32_e32 v104, v2
	v_mov_b32_e32 v105, v2
	v_mov_b32_e32 v98, v2
	v_mov_b32_e32 v99, v2
	v_mov_b32_e32 v100, v2
	v_mov_b32_e32 v101, v2
	v_mov_b32_e32 v118, v2
	v_mov_b32_e32 v119, v2
	v_mov_b32_e32 v120, v2
	v_mov_b32_e32 v121, v2
	v_mov_b32_e32 v114, v2
	v_mov_b32_e32 v115, v2
	v_mov_b32_e32 v116, v2
	v_mov_b32_e32 v117, v2
	v_mov_b32_e32 v78, v2
	v_mov_b32_e32 v79, v2
	v_mov_b32_e32 v80, v2
	v_mov_b32_e32 v81, v2
	v_mov_b32_e32 v74, v2
	v_mov_b32_e32 v75, v2
	v_mov_b32_e32 v76, v2
	v_mov_b32_e32 v77, v2
	v_mov_b32_e32 v94, v2
	v_mov_b32_e32 v95, v2
	v_mov_b32_e32 v96, v2
	v_mov_b32_e32 v97, v2
	v_mov_b32_e32 v90, v2
	v_mov_b32_e32 v91, v2
	v_mov_b32_e32 v92, v2
	v_mov_b32_e32 v93, v2
	v_mov_b32_e32 v110, v2
	v_mov_b32_e32 v111, v2
	v_mov_b32_e32 v112, v2
	v_mov_b32_e32 v113, v2
	v_mov_b32_e32 v106, v2
	v_mov_b32_e32 v107, v2
	v_mov_b32_e32 v108, v2
	v_mov_b32_e32 v109, v2
	v_mov_b32_e32 v126, v2
	v_mov_b32_e32 v127, v2
	v_mov_b32_e32 v128, v2
	v_mov_b32_e32 v129, v2
	v_mov_b32_e32 v122, v2
	v_mov_b32_e32 v123, v2
	v_mov_b32_e32 v124, v2
	v_mov_b32_e32 v125, v2
	s_mov_b64 s[74:75], 0x80
.LBB0_239:
	s_add_i32 s41, s16, 2
	s_add_u32 s17, s14, 0xfffc0080
	s_addc_u32 s18, s15, -1
	s_add_i32 s42, 0, 0x10000
	v_add_u32_e32 v149, s42, v1
	ds_read_b128 v[156:159], v149
	ds_read_b128 v[160:163], v149 offset:1024
	ds_read_b128 v[164:167], v149 offset:2048
	ds_read_b128 v[168:171], v149 offset:3072
	s_cmp_eq_u32 s31, s16
	s_cselect_b32 s16, s38, s39
	s_cselect_b32 s19, s7, s18
	s_cselect_b32 s18, s9, s17
	s_cselect_b32 s17, s37, s40
	v_lshl_add_u64 v[204:205], s[14:15], 0, v[140:141]
	s_add_i32 m0, s23, 0xc000
	ds_read_b128 v[172:175], v151
	ds_read_b128 v[176:179], v151 offset:1024
	ds_read_b128 v[180:183], v151 offset:2048
	ds_read_b128 v[184:187], v151 offset:3072
	ds_read_b128 v[188:191], v151 offset:4096
	ds_read_b128 v[192:195], v151 offset:5120
	ds_read_b128 v[196:199], v151 offset:6144
	ds_read_b128 v[200:203], v151 offset:7168
	global_load_lds_dwordx4 v[204:205], off
	v_lshl_add_u64 v[204:205], s[14:15], 0, v[142:143]
	s_add_i32 m0, s23, 0xe000
	s_nop 0
	global_load_lds_dwordx4 v[204:205], off
	s_waitcnt lgkmcnt(8)
	s_barrier
	s_waitcnt lgkmcnt(0)
	s_setprio 1
	s_waitcnt lgkmcnt(0)
	v_mfma_f32_16x16x32_bf16 v[122:125], v[156:159], v[172:175], v[122:125]
	v_mfma_f32_16x16x32_bf16 v[126:129], v[164:167], v[172:175], v[126:129]
	v_mfma_f32_16x16x32_bf16 v[106:109], v[156:159], v[180:183], v[106:109]
	v_mfma_f32_16x16x32_bf16 v[110:113], v[164:167], v[180:183], v[110:113]
	v_mfma_f32_16x16x32_bf16 v[90:93], v[156:159], v[188:191], v[90:93]
	v_mfma_f32_16x16x32_bf16 v[94:97], v[164:167], v[188:191], v[94:97]
	v_mfma_f32_16x16x32_bf16 v[74:77], v[156:159], v[196:199], v[74:77]
	v_mfma_f32_16x16x32_bf16 v[78:81], v[164:167], v[196:199], v[78:81]
	v_mfma_f32_16x16x32_bf16 v[122:125], v[160:163], v[176:179], v[122:125]
	v_mfma_f32_16x16x32_bf16 v[126:129], v[168:171], v[176:179], v[126:129]
	v_mfma_f32_16x16x32_bf16 v[106:109], v[160:163], v[184:187], v[106:109]
	v_mfma_f32_16x16x32_bf16 v[110:113], v[168:171], v[184:187], v[110:113]
	v_mfma_f32_16x16x32_bf16 v[90:93], v[160:163], v[192:195], v[90:93]
	v_mfma_f32_16x16x32_bf16 v[94:97], v[168:171], v[192:195], v[94:97]
	v_mfma_f32_16x16x32_bf16 v[74:77], v[160:163], v[200:203], v[74:77]
	v_mfma_f32_16x16x32_bf16 v[78:81], v[168:171], v[200:203], v[78:81]
	s_setprio 0
	s_barrier
	s_add_i32 s44, 0, 0x14000
	s_add_i32 s42, s42, s22
	v_add_u32_e32 v149, s44, v1
	v_lshl_add_u64 v[230:231], s[16:17], 0, v[134:135]
	s_mov_b32 m0, s42
	ds_read_b128 v[204:207], v149
	ds_read_b128 v[208:211], v149 offset:1024
	ds_read_b128 v[212:215], v149 offset:2048
	ds_read_b128 v[226:229], v149 offset:3072
	global_load_lds_dwordx4 v[230:231], off
	v_lshl_add_u64 v[232:233], s[16:17], 0, v[130:131]
	s_add_i32 m0, s42, 0x2000
	s_nop 0
	global_load_lds_dwordx4 v[232:233], off
	s_barrier
	s_waitcnt lgkmcnt(0)
	s_setprio 1
	s_waitcnt lgkmcnt(0)
	v_mfma_f32_16x16x32_bf16 v[114:117], v[204:207], v[172:175], v[114:117]
	v_mfma_f32_16x16x32_bf16 v[118:121], v[212:215], v[172:175], v[118:121]
	v_mfma_f32_16x16x32_bf16 v[98:101], v[204:207], v[180:183], v[98:101]
	v_mfma_f32_16x16x32_bf16 v[102:105], v[212:215], v[180:183], v[102:105]
	v_mfma_f32_16x16x32_bf16 v[82:85], v[204:207], v[188:191], v[82:85]
	v_mfma_f32_16x16x32_bf16 v[86:89], v[212:215], v[188:191], v[86:89]
	v_mfma_f32_16x16x32_bf16 v[66:69], v[204:207], v[196:199], v[66:69]
	v_mfma_f32_16x16x32_bf16 v[70:73], v[212:215], v[196:199], v[70:73]
	v_mfma_f32_16x16x32_bf16 v[114:117], v[208:211], v[176:179], v[114:117]
	v_mfma_f32_16x16x32_bf16 v[118:121], v[226:229], v[176:179], v[118:121]
	v_mfma_f32_16x16x32_bf16 v[98:101], v[208:211], v[184:187], v[98:101]
	v_mfma_f32_16x16x32_bf16 v[102:105], v[226:229], v[184:187], v[102:105]
	v_mfma_f32_16x16x32_bf16 v[82:85], v[208:211], v[192:195], v[82:85]
	v_mfma_f32_16x16x32_bf16 v[86:89], v[226:229], v[192:195], v[86:89]
	v_mfma_f32_16x16x32_bf16 v[66:69], v[208:211], v[200:203], v[66:69]
	v_mfma_f32_16x16x32_bf16 v[70:73], v[226:229], v[200:203], v[70:73]
	s_setprio 0
	s_mov_b32 m0, s23
	v_lshl_add_u64 v[234:235], s[18:19], 0, v[136:137]
	s_barrier
	ds_read_b128 v[172:175], v151 offset:16384
	ds_read_b128 v[176:179], v151 offset:17408
	ds_read_b128 v[180:183], v151 offset:18432
	ds_read_b128 v[184:187], v151 offset:19456
	ds_read_b128 v[188:191], v151 offset:20480
	ds_read_b128 v[192:195], v151 offset:21504
	ds_read_b128 v[196:199], v151 offset:22528
	ds_read_b128 v[200:203], v151 offset:23552
	global_load_lds_dwordx4 v[234:235], off
	v_lshl_add_u64 v[236:237], s[18:19], 0, v[132:133]
	s_mov_b32 m0, s24
	s_nop 0
	global_load_lds_dwordx4 v[236:237], off
	s_barrier
	s_waitcnt lgkmcnt(0)
	s_setprio 1
	s_waitcnt lgkmcnt(0)
	v_mfma_f32_16x16x32_bf16 v[58:61], v[156:159], v[172:175], v[58:61]
	v_mfma_f32_16x16x32_bf16 v[62:65], v[164:167], v[172:175], v[62:65]
	v_mfma_f32_16x16x32_bf16 v[42:45], v[156:159], v[180:183], v[42:45]
	v_mfma_f32_16x16x32_bf16 v[46:49], v[164:167], v[180:183], v[46:49]
	v_mfma_f32_16x16x32_bf16 v[26:29], v[156:159], v[188:191], v[26:29]
	v_mfma_f32_16x16x32_bf16 v[30:33], v[164:167], v[188:191], v[30:33]
	v_mfma_f32_16x16x32_bf16 v[10:13], v[156:159], v[196:199], v[10:13]
	v_mfma_f32_16x16x32_bf16 v[14:17], v[164:167], v[196:199], v[14:17]
	v_mfma_f32_16x16x32_bf16 v[58:61], v[160:163], v[176:179], v[58:61]
	v_mfma_f32_16x16x32_bf16 v[62:65], v[168:171], v[176:179], v[62:65]
	v_mfma_f32_16x16x32_bf16 v[42:45], v[160:163], v[184:187], v[42:45]
	v_mfma_f32_16x16x32_bf16 v[46:49], v[168:171], v[184:187], v[46:49]
	v_mfma_f32_16x16x32_bf16 v[26:29], v[160:163], v[192:195], v[26:29]
	v_mfma_f32_16x16x32_bf16 v[30:33], v[168:171], v[192:195], v[30:33]
	v_mfma_f32_16x16x32_bf16 v[10:13], v[160:163], v[200:203], v[10:13]
	v_mfma_f32_16x16x32_bf16 v[14:17], v[168:171], v[200:203], v[14:17]
	s_setprio 0
	s_barrier
	s_add_u32 s42, s16, 0x40000
	s_addc_u32 s43, s17, 0
	s_add_i32 s44, s44, s22
	v_lshl_add_u64 v[156:157], s[42:43], 0, v[134:135]
	s_mov_b32 m0, s44
	s_nop 0
	global_load_lds_dwordx4 v[156:157], off
	v_lshl_add_u64 v[156:157], s[42:43], 0, v[130:131]
	s_add_i32 m0, s44, 0x2000
	s_nop 0
	global_load_lds_dwordx4 v[156:157], off
	s_cmp_eq_u32 s100, 0
	s_cbranch_scc1 .Lip_w4n
	s_waitcnt vmcnt(24)
	s_branch .Lip_w4d
.Lip_w4n:
	s_waitcnt vmcnt(6)
.Lip_w4d:
	s_barrier
	s_setprio 1
	v_mfma_f32_16x16x32_bf16 v[50:53], v[204:207], v[172:175], v[50:53]
	v_mfma_f32_16x16x32_bf16 v[54:57], v[212:215], v[172:175], v[54:57]
	v_mfma_f32_16x16x32_bf16 v[34:37], v[204:207], v[180:183], v[34:37]
	v_mfma_f32_16x16x32_bf16 v[38:41], v[212:215], v[180:183], v[38:41]
	v_mfma_f32_16x16x32_bf16 v[18:21], v[204:207], v[188:191], v[18:21]
	v_mfma_f32_16x16x32_bf16 v[22:25], v[212:215], v[188:191], v[22:25]
	v_mfma_f32_16x16x32_bf16 v[6:9], v[204:207], v[196:199], v[6:9]
	v_mfma_f32_16x16x32_bf16 v[2:5], v[212:215], v[196:199], v[2:5]
	v_mfma_f32_16x16x32_bf16 v[50:53], v[208:211], v[176:179], v[50:53]
	v_mfma_f32_16x16x32_bf16 v[54:57], v[226:229], v[176:179], v[54:57]
	v_mfma_f32_16x16x32_bf16 v[34:37], v[208:211], v[184:187], v[34:37]
	v_mfma_f32_16x16x32_bf16 v[38:41], v[226:229], v[184:187], v[38:41]
	v_mfma_f32_16x16x32_bf16 v[18:21], v[208:211], v[192:195], v[18:21]
	v_mfma_f32_16x16x32_bf16 v[22:25], v[226:229], v[192:195], v[22:25]
	v_mfma_f32_16x16x32_bf16 v[6:9], v[208:211], v[200:203], v[6:9]
	v_mfma_f32_16x16x32_bf16 v[2:5], v[226:229], v[200:203], v[2:5]
	s_setprio 0
	s_add_i32 s42, 0, 0x18000
	v_add_u32_e32 v149, s42, v1
	s_barrier
	ds_read_b128 v[156:159], v149
	ds_read_b128 v[160:163], v149 offset:1024
	ds_read_b128 v[164:167], v149 offset:2048
	ds_read_b128 v[168:171], v149 offset:3072
	s_add_u32 s18, s18, 0x40000
	s_addc_u32 s19, s19, 0
	s_mov_b32 m0, s25
	v_lshl_add_u64 v[204:205], s[18:19], 0, v[136:137]
	ds_read_b128 v[172:175], v151 offset:32768
	ds_read_b128 v[176:179], v151 offset:33792
	ds_read_b128 v[180:183], v151 offset:34816
	ds_read_b128 v[184:187], v151 offset:35840
	ds_read_b128 v[188:191], v151 offset:36864
	ds_read_b128 v[192:195], v151 offset:37888
	ds_read_b128 v[196:199], v151 offset:38912
	ds_read_b128 v[200:203], v151 offset:39936
	global_load_lds_dwordx4 v[204:205], off
	v_lshl_add_u64 v[204:205], s[18:19], 0, v[132:133]
	s_mov_b32 m0, s26
	s_nop 0
	global_load_lds_dwordx4 v[204:205], off
	s_waitcnt lgkmcnt(8)
	s_barrier
	s_waitcnt lgkmcnt(0)
	s_setprio 1
	s_waitcnt lgkmcnt(0)
	v_mfma_f32_16x16x32_bf16 v[122:125], v[156:159], v[172:175], v[122:125]
	v_mfma_f32_16x16x32_bf16 v[126:129], v[164:167], v[172:175], v[126:129]
	v_mfma_f32_16x16x32_bf16 v[106:109], v[156:159], v[180:183], v[106:109]
	v_mfma_f32_16x16x32_bf16 v[110:113], v[164:167], v[180:183], v[110:113]
	v_mfma_f32_16x16x32_bf16 v[90:93], v[156:159], v[188:191], v[90:93]
	v_mfma_f32_16x16x32_bf16 v[94:97], v[164:167], v[188:191], v[94:97]
	v_mfma_f32_16x16x32_bf16 v[74:77], v[156:159], v[196:199], v[74:77]
	v_mfma_f32_16x16x32_bf16 v[78:81], v[164:167], v[196:199], v[78:81]
	v_mfma_f32_16x16x32_bf16 v[122:125], v[160:163], v[176:179], v[122:125]
	v_mfma_f32_16x16x32_bf16 v[126:129], v[168:171], v[176:179], v[126:129]
	v_mfma_f32_16x16x32_bf16 v[106:109], v[160:163], v[184:187], v[106:109]
	v_mfma_f32_16x16x32_bf16 v[110:113], v[168:171], v[184:187], v[110:113]
	v_mfma_f32_16x16x32_bf16 v[90:93], v[160:163], v[192:195], v[90:93]
	v_mfma_f32_16x16x32_bf16 v[94:97], v[168:171], v[192:195], v[94:97]
	v_mfma_f32_16x16x32_bf16 v[74:77], v[160:163], v[200:203], v[74:77]
	v_mfma_f32_16x16x32_bf16 v[78:81], v[168:171], v[200:203], v[78:81]
	s_setprio 0
	s_barrier
	s_add_i32 s18, 0, 0x1c000
	s_add_i32 s19, s42, s22
	v_add_u32_e32 v149, s18, v1
	v_lshl_add_u64 v[230:231], v[230:231], 0, s[74:75]
	s_mov_b32 m0, s19
	ds_read_b128 v[204:207], v149
	ds_read_b128 v[208:211], v149 offset:1024
	ds_read_b128 v[212:215], v149 offset:2048
	ds_read_b128 v[226:229], v149 offset:3072
	global_load_lds_dwordx4 v[230:231], off
	v_lshl_add_u64 v[230:231], v[232:233], 0, s[74:75]
	s_add_i32 m0, s19, 0x2000
	s_nop 0
	global_load_lds_dwordx4 v[230:231], off
	s_cmp_eq_u32 s100, 0
	s_cbranch_scc1 .Lip_w6n
	s_waitcnt vmcnt(10)
	s_mov_b32 s100, 0
.Lip_w6n:
	s_barrier
	s_waitcnt lgkmcnt(0)
	s_setprio 1
	s_waitcnt lgkmcnt(0)
	v_mfma_f32_16x16x32_bf16 v[114:117], v[204:207], v[172:175], v[114:117]
	v_mfma_f32_16x16x32_bf16 v[118:121], v[212:215], v[172:175], v[118:121]
	v_mfma_f32_16x16x32_bf16 v[98:101], v[204:207], v[180:183], v[98:101]
	v_mfma_f32_16x16x32_bf16 v[102:105], v[212:215], v[180:183], v[102:105]
	v_mfma_f32_16x16x32_bf16 v[82:85], v[204:207], v[188:191], v[82:85]
	v_mfma_f32_16x16x32_bf16 v[86:89], v[212:215], v[188:191], v[86:89]
	v_mfma_f32_16x16x32_bf16 v[66:69], v[204:207], v[196:199], v[66:69]
	v_mfma_f32_16x16x32_bf16 v[70:73], v[212:215], v[196:199], v[70:73]
	v_mfma_f32_16x16x32_bf16 v[114:117], v[208:211], v[176:179], v[114:117]
	v_mfma_f32_16x16x32_bf16 v[118:121], v[226:229], v[176:179], v[118:121]
	v_mfma_f32_16x16x32_bf16 v[98:101], v[208:211], v[184:187], v[98:101]
	v_mfma_f32_16x16x32_bf16 v[102:105], v[226:229], v[184:187], v[102:105]
	v_mfma_f32_16x16x32_bf16 v[82:85], v[208:211], v[192:195], v[82:85]
	v_mfma_f32_16x16x32_bf16 v[86:89], v[226:229], v[192:195], v[86:89]
	v_mfma_f32_16x16x32_bf16 v[66:69], v[208:211], v[200:203], v[66:69]
	v_mfma_f32_16x16x32_bf16 v[70:73], v[226:229], v[200:203], v[70:73]
	s_setprio 0
	s_mov_b32 m0, s28
	v_lshl_add_u64 v[230:231], v[234:235], 0, s[74:75]
	s_barrier
	ds_read_b128 v[172:175], v151 offset:49152
	ds_read_b128 v[176:179], v151 offset:50176
	ds_read_b128 v[180:183], v151 offset:51200
	ds_read_b128 v[184:187], v151 offset:52224
	ds_read_b128 v[188:191], v151 offset:53248
	ds_read_b128 v[192:195], v151 offset:54272
	ds_read_b128 v[196:199], v151 offset:55296
	ds_read_b128 v[200:203], v151 offset:56320
	global_load_lds_dwordx4 v[230:231], off
	v_lshl_add_u64 v[230:231], v[236:237], 0, s[74:75]
	s_mov_b32 m0, s29
	s_nop 0
	global_load_lds_dwordx4 v[230:231], off
	s_barrier
	s_waitcnt lgkmcnt(0)
	s_setprio 1
	s_waitcnt lgkmcnt(0)
	v_mfma_f32_16x16x32_bf16 v[58:61], v[156:159], v[172:175], v[58:61]
	v_mfma_f32_16x16x32_bf16 v[62:65], v[164:167], v[172:175], v[62:65]
	v_mfma_f32_16x16x32_bf16 v[42:45], v[156:159], v[180:183], v[42:45]
	v_mfma_f32_16x16x32_bf16 v[46:49], v[164:167], v[180:183], v[46:49]
	v_mfma_f32_16x16x32_bf16 v[26:29], v[156:159], v[188:191], v[26:29]
	v_mfma_f32_16x16x32_bf16 v[30:33], v[164:167], v[188:191], v[30:33]
	v_mfma_f32_16x16x32_bf16 v[10:13], v[156:159], v[196:199], v[10:13]
	v_mfma_f32_16x16x32_bf16 v[14:17], v[164:167], v[196:199], v[14:17]
	v_mfma_f32_16x16x32_bf16 v[58:61], v[160:163], v[176:179], v[58:61]
	v_mfma_f32_16x16x32_bf16 v[62:65], v[168:171], v[176:179], v[62:65]
	v_mfma_f32_16x16x32_bf16 v[42:45], v[160:163], v[184:187], v[42:45]
	v_mfma_f32_16x16x32_bf16 v[46:49], v[168:171], v[184:187], v[46:49]
	v_mfma_f32_16x16x32_bf16 v[26:29], v[160:163], v[192:195], v[26:29]
	v_mfma_f32_16x16x32_bf16 v[30:33], v[168:171], v[192:195], v[30:33]
	v_mfma_f32_16x16x32_bf16 v[10:13], v[160:163], v[200:203], v[10:13]
	v_mfma_f32_16x16x32_bf16 v[14:17], v[168:171], v[200:203], v[14:17]
	s_setprio 0
	s_barrier
	s_add_u32 s16, s16, 0x40080
	s_addc_u32 s17, s17, 0
	s_add_i32 s18, s18, s22
	v_lshl_add_u64 v[156:157], s[16:17], 0, v[134:135]
	s_mov_b32 m0, s18
	s_nop 0
	global_load_lds_dwordx4 v[156:157], off
	v_lshl_add_u64 v[156:157], s[16:17], 0, v[130:131]
	s_add_i32 m0, s18, 0x2000
	s_nop 0
	global_load_lds_dwordx4 v[156:157], off
	s_waitcnt vmcnt(6)
	s_barrier
	s_setprio 1
	v_mfma_f32_16x16x32_bf16 v[50:53], v[204:207], v[172:175], v[50:53]
	v_mfma_f32_16x16x32_bf16 v[54:57], v[212:215], v[172:175], v[54:57]
	v_mfma_f32_16x16x32_bf16 v[34:37], v[204:207], v[180:183], v[34:37]
	v_mfma_f32_16x16x32_bf16 v[38:41], v[212:215], v[180:183], v[38:41]
	v_mfma_f32_16x16x32_bf16 v[18:21], v[204:207], v[188:191], v[18:21]
	v_mfma_f32_16x16x32_bf16 v[22:25], v[212:215], v[188:191], v[22:25]
	v_mfma_f32_16x16x32_bf16 v[6:9], v[204:207], v[196:199], v[6:9]
	v_mfma_f32_16x16x32_bf16 v[2:5], v[212:215], v[196:199], v[2:5]
	v_mfma_f32_16x16x32_bf16 v[50:53], v[208:211], v[176:179], v[50:53]
	v_mfma_f32_16x16x32_bf16 v[54:57], v[226:229], v[176:179], v[54:57]
	v_mfma_f32_16x16x32_bf16 v[34:37], v[208:211], v[184:187], v[34:37]
	v_mfma_f32_16x16x32_bf16 v[38:41], v[226:229], v[184:187], v[38:41]
	v_mfma_f32_16x16x32_bf16 v[18:21], v[208:211], v[192:195], v[18:21]
	v_mfma_f32_16x16x32_bf16 v[22:25], v[226:229], v[192:195], v[22:25]
	v_mfma_f32_16x16x32_bf16 v[6:9], v[208:211], v[200:203], v[6:9]
	v_mfma_f32_16x16x32_bf16 v[2:5], v[226:229], v[200:203], v[2:5]
	s_setprio 0
	s_add_u32 s14, s14, 0x100
	s_addc_u32 s15, s15, 0
	s_add_u32 s39, s39, 0x100
	s_addc_u32 s40, s40, 0
	s_cmp_ge_i32 s41, s27
	s_mov_b32 s16, s41
	s_barrier
	s_cbranch_scc0 .LBB0_239
	v_readlane_b32 s38, v255, 8
	v_mov_b32_e32 v203, v155
	v_readlane_b32 s39, v255, 9
	s_cmp_lt_i32 s35, 32
	s_mov_b64 s[14:15], -1
	s_cbranch_scc1 .LBB0_243

.Lzk_2:
	v_mov_b32_e32 v125, 0
	v_mov_b32_e32 v124, v125
	v_mov_b32_e32 v123, v125
	v_mov_b32_e32 v122, v125
	v_mov_b32_e32 v129, v125
	v_mov_b32_e32 v128, v125
	v_mov_b32_e32 v127, v125
	v_mov_b32_e32 v126, v125
	v_mov_b32_e32 v109, v125
	v_mov_b32_e32 v108, v125
	v_mov_b32_e32 v107, v125
	v_mov_b32_e32 v106, v125
	v_mov_b32_e32 v113, v125
	v_mov_b32_e32 v112, v125
	v_mov_b32_e32 v111, v125
	v_mov_b32_e32 v110, v125
	v_mov_b32_e32 v93, v125
	v_mov_b32_e32 v92, v125
	v_mov_b32_e32 v91, v125
	v_mov_b32_e32 v90, v125
	v_mov_b32_e32 v97, v125
	v_mov_b32_e32 v96, v125
	v_mov_b32_e32 v95, v125
	v_mov_b32_e32 v94, v125
	v_mov_b32_e32 v77, v125
	v_mov_b32_e32 v76, v125
	v_mov_b32_e32 v75, v125
	v_mov_b32_e32 v74, v125
	v_mov_b32_e32 v81, v125
	v_mov_b32_e32 v80, v125
	v_mov_b32_e32 v79, v125
	v_mov_b32_e32 v78, v125
	v_mov_b32_e32 v117, v125
	v_mov_b32_e32 v116, v125
	v_mov_b32_e32 v115, v125
	v_mov_b32_e32 v114, v125
	v_mov_b32_e32 v121, v125
	v_mov_b32_e32 v120, v125
	v_mov_b32_e32 v119, v125
	v_mov_b32_e32 v118, v125
	v_mov_b32_e32 v101, v125
	v_mov_b32_e32 v100, v125
	v_mov_b32_e32 v99, v125
	v_mov_b32_e32 v98, v125
	v_mov_b32_e32 v105, v125
	v_mov_b32_e32 v104, v125
	v_mov_b32_e32 v103, v125
	v_mov_b32_e32 v102, v125
	v_mov_b32_e32 v85, v125
	v_mov_b32_e32 v84, v125
	v_mov_b32_e32 v83, v125
	v_mov_b32_e32 v82, v125
	v_mov_b32_e32 v89, v125
	v_mov_b32_e32 v88, v125
	v_mov_b32_e32 v87, v125
	v_mov_b32_e32 v86, v125
	v_mov_b32_e32 v69, v125
	v_mov_b32_e32 v68, v125
	v_mov_b32_e32 v67, v125
	v_mov_b32_e32 v66, v125
	v_mov_b32_e32 v73, v125
	v_mov_b32_e32 v72, v125
	v_mov_b32_e32 v71, v125
	v_mov_b32_e32 v70, v125
	v_mov_b32_e32 v61, v125
	v_mov_b32_e32 v60, v125
	v_mov_b32_e32 v59, v125
	v_mov_b32_e32 v58, v125
	v_mov_b32_e32 v65, v125
	v_mov_b32_e32 v64, v125
	v_mov_b32_e32 v63, v125
	v_mov_b32_e32 v62, v125
	v_mov_b32_e32 v45, v125
	v_mov_b32_e32 v44, v125
	v_mov_b32_e32 v43, v125
	v_mov_b32_e32 v42, v125
	v_mov_b32_e32 v49, v125
	v_mov_b32_e32 v48, v125
	v_mov_b32_e32 v47, v125
	v_mov_b32_e32 v46, v125
	v_mov_b32_e32 v29, v125
	v_mov_b32_e32 v28, v125
	v_mov_b32_e32 v27, v125
	v_mov_b32_e32 v26, v125
	v_mov_b32_e32 v33, v125
	v_mov_b32_e32 v32, v125
	v_mov_b32_e32 v31, v125
	v_mov_b32_e32 v30, v125
	v_mov_b32_e32 v13, v125
	v_mov_b32_e32 v12, v125
	v_mov_b32_e32 v11, v125
	v_mov_b32_e32 v10, v125
	v_mov_b32_e32 v17, v125
	v_mov_b32_e32 v16, v125
	v_mov_b32_e32 v15, v125
	v_mov_b32_e32 v14, v125
	v_mov_b32_e32 v53, v125
	v_mov_b32_e32 v52, v125
	v_mov_b32_e32 v51, v125
	v_mov_b32_e32 v50, v125
	v_mov_b32_e32 v57, v125
	v_mov_b32_e32 v56, v125
	v_mov_b32_e32 v55, v125
	v_mov_b32_e32 v54, v125
	v_mov_b32_e32 v37, v125
	v_mov_b32_e32 v36, v125
	v_mov_b32_e32 v35, v125
	v_mov_b32_e32 v34, v125
	v_mov_b32_e32 v41, v125
	v_mov_b32_e32 v40, v125
	v_mov_b32_e32 v39, v125
	v_mov_b32_e32 v38, v125
	v_mov_b32_e32 v21, v125
	v_mov_b32_e32 v20, v125
	v_mov_b32_e32 v19, v125
	v_mov_b32_e32 v18, v125
	v_mov_b32_e32 v25, v125
	v_mov_b32_e32 v24, v125
	v_mov_b32_e32 v23, v125
	v_mov_b32_e32 v22, v125
	v_mov_b32_e32 v9, v125
	v_mov_b32_e32 v8, v125
	v_mov_b32_e32 v7, v125
	v_mov_b32_e32 v6, v125
	v_mov_b32_e32 v5, v125
	v_mov_b32_e32 v4, v125
	v_mov_b32_e32 v3, v125
	v_mov_b32_e32 v2, v125
	s_branch .LBB0_242

.LBB0_243:
	v_lshl_add_u32 v149, s36, 8, v150
	v_mov_b64_e32 v[156:157], s[50:51]
	s_movk_i32 s7, 0x6000
	v_mad_i64_i32 v[156:157], s[14:15], v149, s7, v[156:157]
	s_lshl_b32 s14, s35, 8
	s_ashr_i32 s15, s14, 31
	v_lshl_add_u64 v[164:165], s[14:15], 1, v[156:157]
	v_cvt_pk_bf16_f32 v159, v128, v129
	v_cvt_pk_bf16_f32 v158, v126, v127
	v_cvt_pk_bf16_f32 v157, v124, v125
	v_cvt_pk_bf16_f32 v156, v122, v123
	v_cvt_pk_bf16_f32 v163, v120, v121
	v_cvt_pk_bf16_f32 v162, v118, v119
	v_cvt_pk_bf16_f32 v161, v116, v117
	v_cvt_pk_bf16_f32 v160, v114, v115
	ds_write_b128 v152, v[156:159]
	ds_write_b128 v153, v[160:163]
	ds_read_b128 v[156:159], v154
	v_lshl_add_u64 v[160:161], v[164:165], 0, s[46:47]
	v_mov_b32_e32 v149, v0
	v_lshl_add_u64 v[164:165], v[160:161], 0, v[148:149]
	ds_read_b128 v[160:163], v154 offset:1024
	s_mov_b32 s7, 0x30000
	s_waitcnt lgkmcnt(0)
	global_store_dwordx4 v[164:165], v[156:159], off
	s_nop 1
	v_add_co_u32_e32 v156, vcc, s7, v164
	v_cvt_pk_bf16_f32 v159, v112, v113
	s_nop 0
	v_addc_co_u32_e32 v157, vcc, 0, v165, vcc
	global_store_dwordx4 v[156:157], v[160:163], off
	v_cvt_pk_bf16_f32 v158, v110, v111
	v_cvt_pk_bf16_f32 v157, v108, v109
	v_cvt_pk_bf16_f32 v156, v106, v107
	v_cvt_pk_bf16_f32 v163, v104, v105
	v_cvt_pk_bf16_f32 v162, v102, v103
	v_cvt_pk_bf16_f32 v161, v100, v101
	v_cvt_pk_bf16_f32 v160, v98, v99
	ds_write_b128 v152, v[156:159]
	ds_write_b128 v153, v[160:163]
	ds_read_b128 v[156:159], v154
	ds_read_b128 v[160:163], v154 offset:1024
	s_mov_b32 s7, 0x60000
	v_add_co_u32_e32 v166, vcc, s7, v164
	s_mov_b32 s7, 0x90000
	s_nop 0
	v_addc_co_u32_e32 v167, vcc, 0, v165, vcc
	s_waitcnt lgkmcnt(0)
	global_store_dwordx4 v[166:167], v[156:159], off
	s_nop 1
	v_add_co_u32_e32 v156, vcc, s7, v164
	v_cvt_pk_bf16_f32 v159, v96, v97
	s_nop 0
	v_addc_co_u32_e32 v157, vcc, 0, v165, vcc
	global_store_dwordx4 v[156:157], v[160:163], off
	v_cvt_pk_bf16_f32 v158, v94, v95
	v_cvt_pk_bf16_f32 v157, v92, v93
	v_cvt_pk_bf16_f32 v156, v90, v91
	v_cvt_pk_bf16_f32 v163, v88, v89
	v_cvt_pk_bf16_f32 v162, v86, v87
	v_cvt_pk_bf16_f32 v161, v84, v85
	v_cvt_pk_bf16_f32 v160, v82, v83
	ds_write_b128 v152, v[156:159]
	ds_write_b128 v153, v[160:163]
	ds_read_b128 v[156:159], v154
	ds_read_b128 v[160:163], v154 offset:1024
	v_add_co_u32_e32 v166, vcc, s62, v164
	s_mov_b32 s7, 0xf0000
	s_nop 0
	v_addc_co_u32_e32 v167, vcc, 0, v165, vcc
	s_waitcnt lgkmcnt(0)
	global_store_dwordx4 v[166:167], v[156:159], off
	s_nop 1
	v_add_co_u32_e32 v156, vcc, s7, v164
	v_cvt_pk_bf16_f32 v159, v80, v81
	s_nop 0
	v_addc_co_u32_e32 v157, vcc, 0, v165, vcc
	global_store_dwordx4 v[156:157], v[160:163], off
	v_cvt_pk_bf16_f32 v158, v78, v79
	v_cvt_pk_bf16_f32 v157, v76, v77
	v_cvt_pk_bf16_f32 v156, v74, v75
	v_cvt_pk_bf16_f32 v163, v72, v73
	v_cvt_pk_bf16_f32 v162, v70, v71
	v_cvt_pk_bf16_f32 v161, v68, v69
	v_cvt_pk_bf16_f32 v160, v66, v67
	ds_write_b128 v152, v[156:159]
	ds_write_b128 v153, v[160:163]
	ds_read_b128 v[156:159], v154
	ds_read_b128 v[160:163], v154 offset:1024
	s_mov_b32 s7, 0x120000
	v_add_co_u32_e32 v166, vcc, s7, v164
	s_mov_b32 s7, 0x150000
	s_nop 0
	v_addc_co_u32_e32 v167, vcc, 0, v165, vcc
	s_waitcnt lgkmcnt(0)
	global_store_dwordx4 v[166:167], v[156:159], off
	s_nop 1
	v_add_co_u32_e32 v156, vcc, s7, v164
	v_cvt_pk_bf16_f32 v159, v64, v65
	s_nop 0
	v_addc_co_u32_e32 v157, vcc, 0, v165, vcc
	global_store_dwordx4 v[156:157], v[160:163], off
	v_cvt_pk_bf16_f32 v158, v62, v63
	v_cvt_pk_bf16_f32 v157, v60, v61
	v_cvt_pk_bf16_f32 v156, v58, v59
	v_cvt_pk_bf16_f32 v163, v56, v57
	v_cvt_pk_bf16_f32 v162, v54, v55
	v_cvt_pk_bf16_f32 v161, v52, v53
	v_cvt_pk_bf16_f32 v160, v50, v51
	ds_write_b128 v152, v[156:159]
	ds_write_b128 v153, v[160:163]
	ds_read_b128 v[156:159], v154
	ds_read_b128 v[160:163], v154 offset:1024
	s_mov_b32 s7, 0x300000
	v_add_co_u32_e32 v166, vcc, s7, v164
	s_mov_b32 s7, 0x330000
	s_nop 0
	v_addc_co_u32_e32 v167, vcc, 0, v165, vcc
	s_waitcnt lgkmcnt(0)
	global_store_dwordx4 v[166:167], v[156:159], off
	s_nop 1
	v_add_co_u32_e32 v156, vcc, s7, v164
	v_cvt_pk_bf16_f32 v159, v48, v49
	s_nop 0
	v_addc_co_u32_e32 v157, vcc, 0, v165, vcc
	global_store_dwordx4 v[156:157], v[160:163], off
	v_cvt_pk_bf16_f32 v158, v46, v47
	v_cvt_pk_bf16_f32 v157, v44, v45
	v_cvt_pk_bf16_f32 v156, v42, v43
	v_cvt_pk_bf16_f32 v163, v40, v41
	v_cvt_pk_bf16_f32 v162, v38, v39
	v_cvt_pk_bf16_f32 v161, v36, v37
	v_cvt_pk_bf16_f32 v160, v34, v35
	ds_write_b128 v152, v[156:159]
	ds_write_b128 v153, v[160:163]
	ds_read_b128 v[156:159], v154
	ds_read_b128 v[160:163], v154 offset:1024
	s_mov_b32 s7, 0x360000
	v_add_co_u32_e32 v166, vcc, s7, v164
	s_mov_b32 s7, 0x390000
	s_nop 0
	v_addc_co_u32_e32 v167, vcc, 0, v165, vcc
	s_waitcnt lgkmcnt(0)
	global_store_dwordx4 v[166:167], v[156:159], off
	s_nop 1
	v_add_co_u32_e32 v156, vcc, s7, v164
	v_cvt_pk_bf16_f32 v159, v32, v33
	s_nop 0
	v_addc_co_u32_e32 v157, vcc, 0, v165, vcc
	global_store_dwordx4 v[156:157], v[160:163], off
	v_cvt_pk_bf16_f32 v158, v30, v31
	v_cvt_pk_bf16_f32 v157, v28, v29
	v_cvt_pk_bf16_f32 v156, v26, v27
	v_cvt_pk_bf16_f32 v163, v24, v25
	v_cvt_pk_bf16_f32 v162, v22, v23
	v_cvt_pk_bf16_f32 v161, v20, v21
	v_cvt_pk_bf16_f32 v160, v18, v19
	ds_write_b128 v152, v[156:159]
	ds_write_b128 v153, v[160:163]
	ds_read_b128 v[156:159], v154
	ds_read_b128 v[160:163], v154 offset:1024
	s_mov_b32 s7, 0x3c0000
	v_add_co_u32_e32 v166, vcc, s7, v164
	s_mov_b32 s7, 0x3f0000
	s_nop 0
	v_addc_co_u32_e32 v167, vcc, 0, v165, vcc
	s_waitcnt lgkmcnt(0)
	global_store_dwordx4 v[166:167], v[156:159], off
	s_nop 1
	v_add_co_u32_e32 v156, vcc, s7, v164
	v_cvt_pk_bf16_f32 v159, v16, v17
	s_nop 0
	v_addc_co_u32_e32 v157, vcc, 0, v165, vcc
	global_store_dwordx4 v[156:157], v[160:163], off
	v_cvt_pk_bf16_f32 v158, v14, v15
	v_cvt_pk_bf16_f32 v157, v12, v13
	v_cvt_pk_bf16_f32 v156, v10, v11
	v_cvt_pk_bf16_f32 v163, v4, v5
	v_cvt_pk_bf16_f32 v162, v2, v3
	v_cvt_pk_bf16_f32 v161, v8, v9
	v_cvt_pk_bf16_f32 v160, v6, v7
	ds_write_b128 v152, v[156:159]
	ds_write_b128 v153, v[160:163]
	ds_read_b128 v[156:159], v154
	ds_read_b128 v[160:163], v154 offset:1024
	v_add_co_u32_e32 v166, vcc, 0x420000, v164
	s_nop 1
	v_addc_co_u32_e32 v167, vcc, 0, v165, vcc
	s_waitcnt lgkmcnt(0)
	global_store_dwordx4 v[166:167], v[156:159], off
	s_nop 1
	v_add_co_u32_e32 v156, vcc, 0x450000, v164
	s_nop 1
	v_addc_co_u32_e32 v157, vcc, 0, v165, vcc
	global_store_dwordx4 v[156:157], v[160:163], off
	s_mov_b32 s100, 1
	s_cbranch_execnz .LBB0_234
.LBB0_244:
	s_lshl_b32 s9, s35, 3
	s_lshl_b32 s7, s36, 7
	s_add_i32 s9, s30, s9
	s_add_i32 s14, s9, s7
	s_ashr_i32 s15, s14, 31
	s_lshl_b64 s[14:15], s[14:15], 14
	v_lshl_add_u64 v[156:157], v[138:139], 0, s[14:15]
	v_cvt_pk_bf16_f32 v97, v96, v97
	v_cvt_pk_bf16_f32 v96, v94, v95
	v_cvt_pk_bf16_f32 v94, v90, v91
	v_add_co_u32_e32 v90, vcc, s63, v156
	s_movk_i32 s7, 0x2000
	s_nop 0
	v_addc_co_u32_e32 v91, vcc, 0, v157, vcc
	v_cvt_pk_bf16_f32 v95, v92, v93
	v_add_co_u32_e32 v92, vcc, s7, v156
	s_movk_i32 s7, 0x3000
	s_nop 0
	v_addc_co_u32_e32 v93, vcc, 0, v157, vcc
	v_cvt_pk_bf16_f32 v33, v32, v33
	v_cvt_pk_bf16_f32 v32, v30, v31
	v_cvt_pk_bf16_f32 v30, v26, v27
	v_add_co_u32_e32 v26, vcc, s7, v156
	v_cvt_pk_bf16_f32 v129, v128, v129
	v_cvt_pk_bf16_f32 v128, v126, v127
	v_cvt_pk_bf16_f32 v127, v124, v125
	v_cvt_pk_bf16_f32 v126, v122, v123
	v_cvt_pk_bf16_f32 v121, v120, v121
	v_cvt_pk_bf16_f32 v120, v118, v119
	v_cvt_pk_bf16_f32 v119, v116, v117
	v_cvt_pk_bf16_f32 v118, v114, v115
	v_cvt_pk_bf16_f32 v113, v112, v113
	v_cvt_pk_bf16_f32 v112, v110, v111
	v_cvt_pk_bf16_f32 v111, v108, v109
	v_cvt_pk_bf16_f32 v110, v106, v107
	v_cvt_pk_bf16_f32 v105, v104, v105
	v_cvt_pk_bf16_f32 v104, v102, v103
	v_cvt_pk_bf16_f32 v103, v100, v101
	v_cvt_pk_bf16_f32 v102, v98, v99
	v_cvt_pk_bf16_f32 v89, v88, v89
	v_cvt_pk_bf16_f32 v88, v86, v87
	v_cvt_pk_bf16_f32 v87, v84, v85
	v_cvt_pk_bf16_f32 v86, v82, v83
	v_cvt_pk_bf16_f32 v81, v80, v81
	v_cvt_pk_bf16_f32 v80, v78, v79
	v_cvt_pk_bf16_f32 v79, v76, v77
	v_cvt_pk_bf16_f32 v78, v74, v75
	v_cvt_pk_bf16_f32 v73, v72, v73
	v_cvt_pk_bf16_f32 v72, v70, v71
	v_cvt_pk_bf16_f32 v71, v68, v69
	v_cvt_pk_bf16_f32 v70, v66, v67
	v_cvt_pk_bf16_f32 v65, v64, v65
	v_cvt_pk_bf16_f32 v64, v62, v63
	v_cvt_pk_bf16_f32 v63, v60, v61
	v_cvt_pk_bf16_f32 v62, v58, v59
	v_cvt_pk_bf16_f32 v57, v56, v57
	v_cvt_pk_bf16_f32 v56, v54, v55
	v_cvt_pk_bf16_f32 v55, v52, v53
	v_cvt_pk_bf16_f32 v54, v50, v51
	v_cvt_pk_bf16_f32 v49, v48, v49
	v_cvt_pk_bf16_f32 v48, v46, v47
	v_cvt_pk_bf16_f32 v47, v44, v45
	v_cvt_pk_bf16_f32 v46, v42, v43
	v_cvt_pk_bf16_f32 v41, v40, v41
	v_cvt_pk_bf16_f32 v40, v38, v39
	v_cvt_pk_bf16_f32 v39, v36, v37
	v_cvt_pk_bf16_f32 v38, v34, v35
	v_cvt_pk_bf16_f32 v31, v28, v29
	v_addc_co_u32_e32 v27, vcc, 0, v157, vcc
	v_cvt_pk_bf16_f32 v25, v24, v25
	v_cvt_pk_bf16_f32 v24, v22, v23
	v_cvt_pk_bf16_f32 v23, v20, v21
	v_cvt_pk_bf16_f32 v22, v18, v19
	v_cvt_pk_bf16_f32 v17, v16, v17
	v_cvt_pk_bf16_f32 v16, v14, v15
	v_cvt_pk_bf16_f32 v15, v12, v13
	v_cvt_pk_bf16_f32 v14, v10, v11
	v_cvt_pk_bf16_f32 v5, v4, v5
	v_cvt_pk_bf16_f32 v4, v2, v3
	v_cvt_pk_bf16_f32 v3, v8, v9
	v_cvt_pk_bf16_f32 v2, v6, v7
	global_store_dwordx4 v[156:157], v[126:129], off
	global_store_dwordx4 v[156:157], v[118:121], off offset:1024
	global_store_dwordx4 v[156:157], v[110:113], off offset:2048
	global_store_dwordx4 v[156:157], v[102:105], off offset:3072
	global_store_dwordx4 v[92:93], v[94:97], off offset:-4096
	global_store_dwordx4 v[90:91], v[86:89], off offset:1024
	global_store_dwordx4 v[90:91], v[78:81], off offset:2048
	global_store_dwordx4 v[90:91], v[70:73], off offset:3072
	global_store_dwordx4 v[92:93], v[62:65], off
	global_store_dwordx4 v[92:93], v[54:57], off offset:1024
	global_store_dwordx4 v[92:93], v[46:49], off offset:2048
	global_store_dwordx4 v[92:93], v[38:41], off offset:3072
	global_store_dwordx4 v[26:27], v[30:33], off
	global_store_dwordx4 v[26:27], v[22:25], off offset:1024
	global_store_dwordx4 v[26:27], v[14:17], off offset:2048
	global_store_dwordx4 v[26:27], v[2:5], off offset:3072
	s_mov_b32 s100, 1
	s_branch .LBB0_234

.LBB0_408:
	s_ashr_i32 s15, s14, 31
	s_lshl_b64 s[16:17], s[14:15], 17
	v_readlane_b32 s13, v254, 21
	s_add_u32 s13, s13, s16
	v_readlane_b32 s15, v254, 22
	s_addc_u32 s15, s15, s17
	s_ashr_i32 s16, s12, 4
	s_ashr_i32 s17, s16, 31
	s_lshl_b64 s[18:19], s[16:17], 8
	s_add_u32 s16, s13, s18
	s_addc_u32 s17, s15, s19
	s_ashr_i32 s13, s12, 31
	s_lshl_b64 s[40:41], s[12:13], 17
	s_add_u32 s13, s24, s40
	s_addc_u32 s15, s25, s41
	s_add_u32 s18, s13, s18
	s_addc_u32 s19, s15, s19
	s_andn2_b64 vcc, exec, s[10:11]
	s_cbranch_vccnz .Lzk_3
	v_mov_b64_e32 v[2:3], 0x500
	v_cmp_lt_i64_e32 vcc, s[22:23], v[2:3]
	s_and_b64 s[22:23], vcc, exec
	s_cselect_b32 s13, s17, s7
	s_cselect_b32 s15, s16, s6
	s_cselect_b32 s40, s19, s21
	s_cselect_b32 s41, s18, s20
	s_add_u32 s6, s6, 0x10080
	s_addc_u32 s7, s7, 0
	s_add_u32 s42, s20, 0x100
	v_mov_b32_e32 v2, 0
	v_mov_b32_e32 v218, 0xff800000
	v_mov_b32_e32 v216, 0xffffff80
	s_addc_u32 s43, s21, 0
	s_mov_b32 s20, 0
	v_mov_b32_e32 v3, v2
	v_mov_b32_e32 v4, v2
	v_mov_b32_e32 v5, v2
	v_mov_b32_e32 v6, v2
	v_mov_b32_e32 v7, v2
	v_mov_b32_e32 v8, v2
	v_mov_b32_e32 v9, v2
	v_mov_b32_e32 v18, v2
	v_mov_b32_e32 v19, v2
	v_mov_b32_e32 v20, v2
	v_mov_b32_e32 v21, v2
	v_mov_b32_e32 v22, v2
	v_mov_b32_e32 v23, v2
	v_mov_b32_e32 v24, v2
	v_mov_b32_e32 v25, v2
	v_mov_b32_e32 v34, v2
	v_mov_b32_e32 v35, v2
	v_mov_b32_e32 v36, v2
	v_mov_b32_e32 v37, v2
	v_mov_b32_e32 v38, v2
	v_mov_b32_e32 v39, v2
	v_mov_b32_e32 v40, v2
	v_mov_b32_e32 v41, v2
	v_mov_b32_e32 v50, v2
	v_mov_b32_e32 v51, v2
	v_mov_b32_e32 v52, v2
	v_mov_b32_e32 v53, v2
	v_mov_b32_e32 v54, v2
	v_mov_b32_e32 v55, v2
	v_mov_b32_e32 v56, v2
	v_mov_b32_e32 v57, v2
	v_mov_b32_e32 v10, v2
	v_mov_b32_e32 v11, v2
	v_mov_b32_e32 v12, v2
	v_mov_b32_e32 v13, v2
	v_mov_b32_e32 v14, v2
	v_mov_b32_e32 v15, v2
	v_mov_b32_e32 v16, v2
	v_mov_b32_e32 v17, v2
	v_mov_b32_e32 v26, v2
	v_mov_b32_e32 v27, v2
	v_mov_b32_e32 v28, v2
	v_mov_b32_e32 v29, v2
	v_mov_b32_e32 v30, v2
	v_mov_b32_e32 v31, v2
	v_mov_b32_e32 v32, v2
	v_mov_b32_e32 v33, v2
	v_mov_b32_e32 v42, v2
	v_mov_b32_e32 v43, v2
	v_mov_b32_e32 v44, v2
	v_mov_b32_e32 v45, v2
	v_mov_b32_e32 v46, v2
	v_mov_b32_e32 v47, v2
	v_mov_b32_e32 v48, v2
	v_mov_b32_e32 v49, v2
	v_mov_b32_e32 v58, v2
	v_mov_b32_e32 v59, v2
	v_mov_b32_e32 v60, v2
	v_mov_b32_e32 v61, v2
	v_mov_b32_e32 v62, v2
	v_mov_b32_e32 v63, v2
	v_mov_b32_e32 v64, v2
	v_mov_b32_e32 v65, v2
	v_mov_b32_e32 v66, v2
	v_mov_b32_e32 v67, v2
	v_mov_b32_e32 v68, v2
	v_mov_b32_e32 v69, v2
	v_mov_b32_e32 v70, v2
	v_mov_b32_e32 v71, v2
	v_mov_b32_e32 v72, v2
	v_mov_b32_e32 v73, v2
	v_mov_b32_e32 v82, v2
	v_mov_b32_e32 v83, v2
	v_mov_b32_e32 v84, v2
	v_mov_b32_e32 v85, v2
	v_mov_b32_e32 v90, v2
	v_mov_b32_e32 v91, v2
	v_mov_b32_e32 v92, v2
	v_mov_b32_e32 v93, v2
	v_mov_b32_e32 v114, v2
	v_mov_b32_e32 v115, v2
	v_mov_b32_e32 v116, v2
	v_mov_b32_e32 v117, v2
	v_mov_b32_e32 v118, v2
	v_mov_b32_e32 v119, v2
	v_mov_b32_e32 v120, v2
	v_mov_b32_e32 v121, v2
	v_mov_b32_e32 v130, v2
	v_mov_b32_e32 v131, v2
	v_mov_b32_e32 v132, v2
	v_mov_b32_e32 v133, v2
	v_mov_b32_e32 v134, v2
	v_mov_b32_e32 v135, v2
	v_mov_b32_e32 v136, v2
	v_mov_b32_e32 v137, v2
	v_mov_b32_e32 v74, v2
	v_mov_b32_e32 v75, v2
	v_mov_b32_e32 v76, v2
	v_mov_b32_e32 v77, v2
	v_mov_b32_e32 v78, v2
	v_mov_b32_e32 v79, v2
	v_mov_b32_e32 v80, v2
	v_mov_b32_e32 v81, v2
	v_mov_b32_e32 v102, v2
	v_mov_b32_e32 v103, v2
	v_mov_b32_e32 v104, v2
	v_mov_b32_e32 v105, v2
	v_mov_b32_e32 v110, v2
	v_mov_b32_e32 v111, v2
	v_mov_b32_e32 v112, v2
	v_mov_b32_e32 v113, v2
	v_mov_b32_e32 v122, v2
	v_mov_b32_e32 v123, v2
	v_mov_b32_e32 v124, v2
	v_mov_b32_e32 v125, v2
	v_mov_b32_e32 v126, v2
	v_mov_b32_e32 v127, v2
	v_mov_b32_e32 v128, v2
	v_mov_b32_e32 v129, v2
	v_mov_b32_e32 v138, v2
	v_mov_b32_e32 v139, v2
	v_mov_b32_e32 v140, v2
	v_mov_b32_e32 v141, v2
	v_mov_b32_e32 v148, v2
	v_mov_b32_e32 v149, v2
	v_mov_b32_e32 v150, v2
	v_mov_b32_e32 v151, v2
	s_mov_b64 s[74:75], 0x80

.Lzk_3:
	v_mov_b32_e32 v151, 0
	v_mov_b32_e32 v150, v151
	v_mov_b32_e32 v149, v151
	v_mov_b32_e32 v148, v151
	v_mov_b32_e32 v141, v151
	v_mov_b32_e32 v140, v151
	v_mov_b32_e32 v139, v151
	v_mov_b32_e32 v138, v151
	v_mov_b32_e32 v129, v151
	v_mov_b32_e32 v128, v151
	v_mov_b32_e32 v127, v151
	v_mov_b32_e32 v126, v151
	v_mov_b32_e32 v125, v151
	v_mov_b32_e32 v124, v151
	v_mov_b32_e32 v123, v151
	v_mov_b32_e32 v122, v151
	v_mov_b32_e32 v113, v151
	v_mov_b32_e32 v112, v151
	v_mov_b32_e32 v111, v151
	v_mov_b32_e32 v110, v151
	v_mov_b32_e32 v105, v151
	v_mov_b32_e32 v104, v151
	v_mov_b32_e32 v103, v151
	v_mov_b32_e32 v102, v151
	v_mov_b32_e32 v81, v151
	v_mov_b32_e32 v80, v151
	v_mov_b32_e32 v79, v151
	v_mov_b32_e32 v78, v151
	v_mov_b32_e32 v77, v151
	v_mov_b32_e32 v76, v151
	v_mov_b32_e32 v75, v151
	v_mov_b32_e32 v74, v151
	v_mov_b32_e32 v137, v151
	v_mov_b32_e32 v136, v151
	v_mov_b32_e32 v135, v151
	v_mov_b32_e32 v134, v151
	v_mov_b32_e32 v133, v151
	v_mov_b32_e32 v132, v151
	v_mov_b32_e32 v131, v151
	v_mov_b32_e32 v130, v151
	v_mov_b32_e32 v121, v151
	v_mov_b32_e32 v120, v151
	v_mov_b32_e32 v119, v151
	v_mov_b32_e32 v118, v151
	v_mov_b32_e32 v117, v151
	v_mov_b32_e32 v116, v151
	v_mov_b32_e32 v115, v151
	v_mov_b32_e32 v114, v151
	v_mov_b32_e32 v93, v151
	v_mov_b32_e32 v92, v151
	v_mov_b32_e32 v91, v151
	v_mov_b32_e32 v90, v151
	v_mov_b32_e32 v85, v151
	v_mov_b32_e32 v84, v151
	v_mov_b32_e32 v83, v151
	v_mov_b32_e32 v82, v151
	v_mov_b32_e32 v73, v151
	v_mov_b32_e32 v72, v151
	v_mov_b32_e32 v71, v151
	v_mov_b32_e32 v70, v151
	v_mov_b32_e32 v69, v151
	v_mov_b32_e32 v68, v151
	v_mov_b32_e32 v67, v151
	v_mov_b32_e32 v66, v151
	v_mov_b32_e32 v65, v151
	v_mov_b32_e32 v64, v151
	v_mov_b32_e32 v63, v151
	v_mov_b32_e32 v62, v151
	v_mov_b32_e32 v61, v151
	v_mov_b32_e32 v60, v151
	v_mov_b32_e32 v59, v151
	v_mov_b32_e32 v58, v151
	v_mov_b32_e32 v49, v151
	v_mov_b32_e32 v48, v151
	v_mov_b32_e32 v47, v151
	v_mov_b32_e32 v46, v151
	v_mov_b32_e32 v45, v151
	v_mov_b32_e32 v44, v151
	v_mov_b32_e32 v43, v151
	v_mov_b32_e32 v42, v151
	v_mov_b32_e32 v33, v151
	v_mov_b32_e32 v32, v151
	v_mov_b32_e32 v31, v151
	v_mov_b32_e32 v30, v151
	v_mov_b32_e32 v29, v151
	v_mov_b32_e32 v28, v151
	v_mov_b32_e32 v27, v151
	v_mov_b32_e32 v26, v151
	v_mov_b32_e32 v17, v151
	v_mov_b32_e32 v16, v151
	v_mov_b32_e32 v15, v151
	v_mov_b32_e32 v14, v151
	v_mov_b32_e32 v13, v151
	v_mov_b32_e32 v12, v151
	v_mov_b32_e32 v11, v151
	v_mov_b32_e32 v10, v151
	v_mov_b32_e32 v57, v151
	v_mov_b32_e32 v56, v151
	v_mov_b32_e32 v55, v151
	v_mov_b32_e32 v54, v151
	v_mov_b32_e32 v53, v151
	v_mov_b32_e32 v52, v151
	v_mov_b32_e32 v51, v151
	v_mov_b32_e32 v50, v151
	v_mov_b32_e32 v41, v151
	v_mov_b32_e32 v40, v151
	v_mov_b32_e32 v39, v151
	v_mov_b32_e32 v38, v151
	v_mov_b32_e32 v37, v151
	v_mov_b32_e32 v36, v151
	v_mov_b32_e32 v35, v151
	v_mov_b32_e32 v34, v151
	v_mov_b32_e32 v25, v151
	v_mov_b32_e32 v24, v151
	v_mov_b32_e32 v23, v151
	v_mov_b32_e32 v22, v151
	v_mov_b32_e32 v21, v151
	v_mov_b32_e32 v20, v151
	v_mov_b32_e32 v19, v151
	v_mov_b32_e32 v18, v151
	v_mov_b32_e32 v9, v151
	v_mov_b32_e32 v8, v151
	v_mov_b32_e32 v7, v151
	v_mov_b32_e32 v6, v151
	v_mov_b32_e32 v5, v151
	v_mov_b32_e32 v4, v151
	v_mov_b32_e32 v3, v151
	v_mov_b32_e32 v2, v151
	s_branch .LBB0_412

.LBB0_1065:
	s_ashr_i32 s11, s10, 31
	s_lshl_b64 s[12:13], s[10:11], 19
	v_readlane_b32 s14, v254, 11
	v_readlane_b32 s15, v254, 12
	s_add_u32 s12, s14, s12
	s_addc_u32 s13, s15, s13
	s_ashr_i32 s9, s8, 31
	s_lshl_b64 s[14:15], s[8:9], 19
	v_mov_b64_e32 v[2:3], 0x100
	s_add_u32 s14, s20, s14
	v_cmp_lt_i64_e64 s[6:7], s[6:7], v[2:3]
	v_mov_b32_e32 v218, 0xff800000
	v_mov_b32_e32 v216, 0xffffff80
	s_addc_u32 s15, s21, s15
	s_andn2_b64 vcc, exec, s[0:1]
	s_cbranch_vccnz .Lzk_4
	s_and_b64 s[6:7], s[6:7], exec
	s_cselect_b32 s9, s13, s19
	s_cselect_b32 s11, s12, s18
	s_cselect_b32 s36, s15, s17
	s_cselect_b32 s37, s14, s16
	s_add_u32 s6, s18, 0x40080
	s_addc_u32 s7, s19, 0
	s_add_u32 s38, s16, 0x100
	v_mov_b32_e32 v2, 0
	s_addc_u32 s39, s17, 0
	s_mov_b32 s16, 0
	v_mov_b32_e32 v3, v2
	v_mov_b32_e32 v4, v2
	v_mov_b32_e32 v5, v2
	v_mov_b32_e32 v6, v2
	v_mov_b32_e32 v7, v2
	v_mov_b32_e32 v8, v2
	v_mov_b32_e32 v9, v2
	v_mov_b32_e32 v18, v2
	v_mov_b32_e32 v19, v2
	v_mov_b32_e32 v20, v2
	v_mov_b32_e32 v21, v2
	v_mov_b32_e32 v22, v2
	v_mov_b32_e32 v23, v2
	v_mov_b32_e32 v24, v2
	v_mov_b32_e32 v25, v2
	v_mov_b32_e32 v34, v2
	v_mov_b32_e32 v35, v2
	v_mov_b32_e32 v36, v2
	v_mov_b32_e32 v37, v2
	v_mov_b32_e32 v38, v2
	v_mov_b32_e32 v39, v2
	v_mov_b32_e32 v40, v2
	v_mov_b32_e32 v41, v2
	v_mov_b32_e32 v50, v2
	v_mov_b32_e32 v51, v2
	v_mov_b32_e32 v52, v2
	v_mov_b32_e32 v53, v2
	v_mov_b32_e32 v54, v2
	v_mov_b32_e32 v55, v2
	v_mov_b32_e32 v56, v2
	v_mov_b32_e32 v57, v2
	v_mov_b32_e32 v10, v2
	v_mov_b32_e32 v11, v2
	v_mov_b32_e32 v12, v2
	v_mov_b32_e32 v13, v2
	v_mov_b32_e32 v14, v2
	v_mov_b32_e32 v15, v2
	v_mov_b32_e32 v16, v2
	v_mov_b32_e32 v17, v2
	v_mov_b32_e32 v26, v2
	v_mov_b32_e32 v27, v2
	v_mov_b32_e32 v28, v2
	v_mov_b32_e32 v29, v2
	v_mov_b32_e32 v30, v2
	v_mov_b32_e32 v31, v2
	v_mov_b32_e32 v32, v2
	v_mov_b32_e32 v33, v2
	v_mov_b32_e32 v42, v2
	v_mov_b32_e32 v43, v2
	v_mov_b32_e32 v44, v2
	v_mov_b32_e32 v45, v2
	v_mov_b32_e32 v46, v2
	v_mov_b32_e32 v47, v2
	v_mov_b32_e32 v48, v2
	v_mov_b32_e32 v49, v2
	v_mov_b32_e32 v58, v2
	v_mov_b32_e32 v59, v2
	v_mov_b32_e32 v60, v2
	v_mov_b32_e32 v61, v2
	v_mov_b32_e32 v62, v2
	v_mov_b32_e32 v63, v2
	v_mov_b32_e32 v64, v2
	v_mov_b32_e32 v65, v2
	v_mov_b32_e32 v66, v2
	v_mov_b32_e32 v67, v2
	v_mov_b32_e32 v68, v2
	v_mov_b32_e32 v69, v2
	v_mov_b32_e32 v70, v2
	v_mov_b32_e32 v71, v2
	v_mov_b32_e32 v72, v2
	v_mov_b32_e32 v73, v2
	v_mov_b32_e32 v82, v2
	v_mov_b32_e32 v83, v2
	v_mov_b32_e32 v84, v2
	v_mov_b32_e32 v85, v2
	v_mov_b32_e32 v86, v2
	v_mov_b32_e32 v87, v2
	v_mov_b32_e32 v88, v2
	v_mov_b32_e32 v89, v2
	v_mov_b32_e32 v98, v2
	v_mov_b32_e32 v99, v2
	v_mov_b32_e32 v100, v2
	v_mov_b32_e32 v101, v2
	v_mov_b32_e32 v102, v2
	v_mov_b32_e32 v103, v2
	v_mov_b32_e32 v104, v2
	v_mov_b32_e32 v105, v2
	v_mov_b32_e32 v114, v2
	v_mov_b32_e32 v115, v2
	v_mov_b32_e32 v116, v2
	v_mov_b32_e32 v117, v2
	v_mov_b32_e32 v118, v2
	v_mov_b32_e32 v119, v2
	v_mov_b32_e32 v120, v2
	v_mov_b32_e32 v121, v2
	v_mov_b32_e32 v74, v2
	v_mov_b32_e32 v75, v2
	v_mov_b32_e32 v76, v2
	v_mov_b32_e32 v77, v2
	v_mov_b32_e32 v78, v2
	v_mov_b32_e32 v79, v2
	v_mov_b32_e32 v80, v2
	v_mov_b32_e32 v81, v2
	v_mov_b32_e32 v90, v2
	v_mov_b32_e32 v91, v2
	v_mov_b32_e32 v92, v2
	v_mov_b32_e32 v93, v2
	v_mov_b32_e32 v94, v2
	v_mov_b32_e32 v95, v2
	v_mov_b32_e32 v96, v2
	v_mov_b32_e32 v97, v2
	v_mov_b32_e32 v106, v2
	v_mov_b32_e32 v107, v2
	v_mov_b32_e32 v108, v2
	v_mov_b32_e32 v109, v2
	v_mov_b32_e32 v110, v2
	v_mov_b32_e32 v111, v2
	v_mov_b32_e32 v112, v2
	v_mov_b32_e32 v113, v2
	v_mov_b32_e32 v122, v2
	v_mov_b32_e32 v123, v2
	v_mov_b32_e32 v124, v2
	v_mov_b32_e32 v125, v2
	v_mov_b32_e32 v126, v2
	v_mov_b32_e32 v127, v2
	v_mov_b32_e32 v128, v2
	v_mov_b32_e32 v129, v2
	s_mov_b64 s[46:47], 0x80

.Lzk_4:
	v_mov_b32_e32 v129, 0
	v_mov_b32_e32 v128, v129
	v_mov_b32_e32 v127, v129
	v_mov_b32_e32 v126, v129
	v_mov_b32_e32 v125, v129
	v_mov_b32_e32 v124, v129
	v_mov_b32_e32 v123, v129
	v_mov_b32_e32 v122, v129
	v_mov_b32_e32 v113, v129
	v_mov_b32_e32 v112, v129
	v_mov_b32_e32 v111, v129
	v_mov_b32_e32 v110, v129
	v_mov_b32_e32 v109, v129
	v_mov_b32_e32 v108, v129
	v_mov_b32_e32 v107, v129
	v_mov_b32_e32 v106, v129
	v_mov_b32_e32 v97, v129
	v_mov_b32_e32 v96, v129
	v_mov_b32_e32 v95, v129
	v_mov_b32_e32 v94, v129
	v_mov_b32_e32 v93, v129
	v_mov_b32_e32 v92, v129
	v_mov_b32_e32 v91, v129
	v_mov_b32_e32 v90, v129
	v_mov_b32_e32 v81, v129
	v_mov_b32_e32 v80, v129
	v_mov_b32_e32 v79, v129
	v_mov_b32_e32 v78, v129
	v_mov_b32_e32 v77, v129
	v_mov_b32_e32 v76, v129
	v_mov_b32_e32 v75, v129
	v_mov_b32_e32 v74, v129
	v_mov_b32_e32 v121, v129
	v_mov_b32_e32 v120, v129
	v_mov_b32_e32 v119, v129
	v_mov_b32_e32 v118, v129
	v_mov_b32_e32 v117, v129
	v_mov_b32_e32 v116, v129
	v_mov_b32_e32 v115, v129
	v_mov_b32_e32 v114, v129
	v_mov_b32_e32 v105, v129
	v_mov_b32_e32 v104, v129
	v_mov_b32_e32 v103, v129
	v_mov_b32_e32 v102, v129
	v_mov_b32_e32 v101, v129
	v_mov_b32_e32 v100, v129
	v_mov_b32_e32 v99, v129
	v_mov_b32_e32 v98, v129
	v_mov_b32_e32 v89, v129
	v_mov_b32_e32 v88, v129
	v_mov_b32_e32 v87, v129
	v_mov_b32_e32 v86, v129
	v_mov_b32_e32 v85, v129
	v_mov_b32_e32 v84, v129
	v_mov_b32_e32 v83, v129
	v_mov_b32_e32 v82, v129
	v_mov_b32_e32 v73, v129
	v_mov_b32_e32 v72, v129
	v_mov_b32_e32 v71, v129
	v_mov_b32_e32 v70, v129
	v_mov_b32_e32 v69, v129
	v_mov_b32_e32 v68, v129
	v_mov_b32_e32 v67, v129
	v_mov_b32_e32 v66, v129
	v_mov_b32_e32 v65, v129
	v_mov_b32_e32 v64, v129
	v_mov_b32_e32 v63, v129
	v_mov_b32_e32 v62, v129
	v_mov_b32_e32 v61, v129
	v_mov_b32_e32 v60, v129
	v_mov_b32_e32 v59, v129
	v_mov_b32_e32 v58, v129
	v_mov_b32_e32 v49, v129
	v_mov_b32_e32 v48, v129
	v_mov_b32_e32 v47, v129
	v_mov_b32_e32 v46, v129
	v_mov_b32_e32 v45, v129
	v_mov_b32_e32 v44, v129
	v_mov_b32_e32 v43, v129
	v_mov_b32_e32 v42, v129
	v_mov_b32_e32 v33, v129
	v_mov_b32_e32 v32, v129
	v_mov_b32_e32 v31, v129
	v_mov_b32_e32 v30, v129
	v_mov_b32_e32 v29, v129
	v_mov_b32_e32 v28, v129
	v_mov_b32_e32 v27, v129
	v_mov_b32_e32 v26, v129
	v_mov_b32_e32 v17, v129
	v_mov_b32_e32 v16, v129
	v_mov_b32_e32 v15, v129
	v_mov_b32_e32 v14, v129
	v_mov_b32_e32 v13, v129
	v_mov_b32_e32 v12, v129
	v_mov_b32_e32 v11, v129
	v_mov_b32_e32 v10, v129
	v_mov_b32_e32 v57, v129
	v_mov_b32_e32 v56, v129
	v_mov_b32_e32 v55, v129
	v_mov_b32_e32 v54, v129
	v_mov_b32_e32 v53, v129
	v_mov_b32_e32 v52, v129
	v_mov_b32_e32 v51, v129
	v_mov_b32_e32 v50, v129
	v_mov_b32_e32 v41, v129
	v_mov_b32_e32 v40, v129
	v_mov_b32_e32 v39, v129
	v_mov_b32_e32 v38, v129
	v_mov_b32_e32 v37, v129
	v_mov_b32_e32 v36, v129
	v_mov_b32_e32 v35, v129
	v_mov_b32_e32 v34, v129
	v_mov_b32_e32 v25, v129
	v_mov_b32_e32 v24, v129
	v_mov_b32_e32 v23, v129
	v_mov_b32_e32 v22, v129
	v_mov_b32_e32 v21, v129
	v_mov_b32_e32 v20, v129
	v_mov_b32_e32 v19, v129
	v_mov_b32_e32 v18, v129
	v_mov_b32_e32 v9, v129
	v_mov_b32_e32 v8, v129
	v_mov_b32_e32 v7, v129
	v_mov_b32_e32 v6, v129
	v_mov_b32_e32 v5, v129
	v_mov_b32_e32 v4, v129
	v_mov_b32_e32 v3, v129
	v_mov_b32_e32 v2, v129
	s_branch .LBB0_1058

.LBB0_1279:
	s_ashr_i32 s5, s4, 31
	s_lshl_b64 s[10:11], s[4:5], 18
	s_add_u32 s10, s50, s10
	s_addc_u32 s11, s51, s11
	s_ashr_i32 s7, s6, 31
	s_lshl_b64 s[12:13], s[6:7], 18
	s_add_u32 s12, s20, s12
	s_addc_u32 s13, s21, s13
	s_andn2_b64 vcc, exec, s[0:1]
	s_cbranch_vccnz .Lzk_5
	s_and_b64 s[18:19], s[18:19], exec
	s_cselect_b32 s5, s11, s15
	s_cselect_b32 s7, s10, s14
	s_cselect_b32 s36, s13, s17
	s_cselect_b32 s37, s12, s16
	s_add_u32 s14, s14, 0x20080
	s_addc_u32 s15, s15, 0
	s_add_u32 s38, s16, 0x100
	v_mov_b32_e32 v18, 0
	v_mov_b32_e32 v218, 0xff800000
	v_mov_b32_e32 v214, 0xffffff80
	s_addc_u32 s39, s17, 0
	s_mov_b32 s16, 0
	v_mov_b32_e32 v19, v18
	v_mov_b32_e32 v20, v18
	v_mov_b32_e32 v21, v18
	v_mov_b32_e32 v26, v18
	v_mov_b32_e32 v27, v18
	v_mov_b32_e32 v28, v18
	v_mov_b32_e32 v29, v18
	v_mov_b32_e32 v34, v18
	v_mov_b32_e32 v35, v18
	v_mov_b32_e32 v36, v18
	v_mov_b32_e32 v37, v18
	v_mov_b32_e32 v42, v18
	v_mov_b32_e32 v43, v18
	v_mov_b32_e32 v44, v18
	v_mov_b32_e32 v45, v18
	v_mov_b32_e32 v50, v18
	v_mov_b32_e32 v51, v18
	v_mov_b32_e32 v52, v18
	v_mov_b32_e32 v53, v18
	v_mov_b32_e32 v58, v18
	v_mov_b32_e32 v59, v18
	v_mov_b32_e32 v60, v18
	v_mov_b32_e32 v61, v18
	v_mov_b32_e32 v66, v18
	v_mov_b32_e32 v67, v18
	v_mov_b32_e32 v68, v18
	v_mov_b32_e32 v69, v18
	v_mov_b32_e32 v74, v18
	v_mov_b32_e32 v75, v18
	v_mov_b32_e32 v76, v18
	v_mov_b32_e32 v77, v18
	v_mov_b32_e32 v22, v18
	v_mov_b32_e32 v23, v18
	v_mov_b32_e32 v24, v18
	v_mov_b32_e32 v25, v18
	v_mov_b32_e32 v30, v18
	v_mov_b32_e32 v31, v18
	v_mov_b32_e32 v32, v18
	v_mov_b32_e32 v33, v18
	v_mov_b32_e32 v38, v18
	v_mov_b32_e32 v39, v18
	v_mov_b32_e32 v40, v18
	v_mov_b32_e32 v41, v18
	v_mov_b32_e32 v46, v18
	v_mov_b32_e32 v47, v18
	v_mov_b32_e32 v48, v18
	v_mov_b32_e32 v49, v18
	v_mov_b32_e32 v54, v18
	v_mov_b32_e32 v55, v18
	v_mov_b32_e32 v56, v18
	v_mov_b32_e32 v57, v18
	v_mov_b32_e32 v62, v18
	v_mov_b32_e32 v63, v18
	v_mov_b32_e32 v64, v18
	v_mov_b32_e32 v65, v18
	v_mov_b32_e32 v70, v18
	v_mov_b32_e32 v71, v18
	v_mov_b32_e32 v72, v18
	v_mov_b32_e32 v73, v18
	v_mov_b32_e32 v78, v18
	v_mov_b32_e32 v79, v18
	v_mov_b32_e32 v80, v18
	v_mov_b32_e32 v81, v18
	v_mov_b32_e32 v82, v18
	v_mov_b32_e32 v83, v18
	v_mov_b32_e32 v84, v18
	v_mov_b32_e32 v85, v18
	v_mov_b32_e32 v90, v18
	v_mov_b32_e32 v91, v18
	v_mov_b32_e32 v92, v18
	v_mov_b32_e32 v93, v18
	v_mov_b32_e32 v98, v18
	v_mov_b32_e32 v99, v18
	v_mov_b32_e32 v100, v18
	v_mov_b32_e32 v101, v18
	v_mov_b32_e32 v106, v18
	v_mov_b32_e32 v107, v18
	v_mov_b32_e32 v108, v18
	v_mov_b32_e32 v109, v18
	v_mov_b32_e32 v114, v18
	v_mov_b32_e32 v115, v18
	v_mov_b32_e32 v116, v18
	v_mov_b32_e32 v117, v18
	v_mov_b32_e32 v122, v18
	v_mov_b32_e32 v123, v18
	v_mov_b32_e32 v124, v18
	v_mov_b32_e32 v125, v18
	v_mov_b32_e32 v130, v18
	v_mov_b32_e32 v131, v18
	v_mov_b32_e32 v132, v18
	v_mov_b32_e32 v133, v18
	v_mov_b32_e32 v138, v18
	v_mov_b32_e32 v139, v18
	v_mov_b32_e32 v140, v18
	v_mov_b32_e32 v141, v18
	v_mov_b32_e32 v86, v18
	v_mov_b32_e32 v87, v18
	v_mov_b32_e32 v88, v18
	v_mov_b32_e32 v89, v18
	v_mov_b32_e32 v94, v18
	v_mov_b32_e32 v95, v18
	v_mov_b32_e32 v96, v18
	v_mov_b32_e32 v97, v18
	v_mov_b32_e32 v102, v18
	v_mov_b32_e32 v103, v18
	v_mov_b32_e32 v104, v18
	v_mov_b32_e32 v105, v18
	v_mov_b32_e32 v110, v18
	v_mov_b32_e32 v111, v18
	v_mov_b32_e32 v112, v18
	v_mov_b32_e32 v113, v18
	v_mov_b32_e32 v118, v18
	v_mov_b32_e32 v119, v18
	v_mov_b32_e32 v120, v18
	v_mov_b32_e32 v121, v18
	v_mov_b32_e32 v126, v18
	v_mov_b32_e32 v127, v18
	v_mov_b32_e32 v128, v18
	v_mov_b32_e32 v129, v18
	v_mov_b32_e32 v134, v18
	v_mov_b32_e32 v135, v18
	v_mov_b32_e32 v136, v18
	v_mov_b32_e32 v137, v18
	v_mov_b32_e32 v148, v18
	v_mov_b32_e32 v149, v18
	v_mov_b32_e32 v150, v18
	v_mov_b32_e32 v151, v18
	s_mov_b64 s[46:47], 0x80

.Lzk_5:
	v_mov_b32_e32 v151, 0
	v_mov_b32_e32 v150, v151
	v_mov_b32_e32 v149, v151
	v_mov_b32_e32 v148, v151
	v_mov_b32_e32 v137, v151
	v_mov_b32_e32 v136, v151
	v_mov_b32_e32 v135, v151
	v_mov_b32_e32 v134, v151
	v_mov_b32_e32 v129, v151
	v_mov_b32_e32 v128, v151
	v_mov_b32_e32 v127, v151
	v_mov_b32_e32 v126, v151
	v_mov_b32_e32 v121, v151
	v_mov_b32_e32 v120, v151
	v_mov_b32_e32 v119, v151
	v_mov_b32_e32 v118, v151
	v_mov_b32_e32 v113, v151
	v_mov_b32_e32 v112, v151
	v_mov_b32_e32 v111, v151
	v_mov_b32_e32 v110, v151
	v_mov_b32_e32 v105, v151
	v_mov_b32_e32 v104, v151
	v_mov_b32_e32 v103, v151
	v_mov_b32_e32 v102, v151
	v_mov_b32_e32 v97, v151
	v_mov_b32_e32 v96, v151
	v_mov_b32_e32 v95, v151
	v_mov_b32_e32 v94, v151
	v_mov_b32_e32 v89, v151
	v_mov_b32_e32 v88, v151
	v_mov_b32_e32 v87, v151
	v_mov_b32_e32 v86, v151
	v_mov_b32_e32 v141, v151
	v_mov_b32_e32 v140, v151
	v_mov_b32_e32 v139, v151
	v_mov_b32_e32 v138, v151
	v_mov_b32_e32 v133, v151
	v_mov_b32_e32 v132, v151
	v_mov_b32_e32 v131, v151
	v_mov_b32_e32 v130, v151
	v_mov_b32_e32 v125, v151
	v_mov_b32_e32 v124, v151
	v_mov_b32_e32 v123, v151
	v_mov_b32_e32 v122, v151
	v_mov_b32_e32 v117, v151
	v_mov_b32_e32 v116, v151
	v_mov_b32_e32 v115, v151
	v_mov_b32_e32 v114, v151
	v_mov_b32_e32 v109, v151
	v_mov_b32_e32 v108, v151
	v_mov_b32_e32 v107, v151
	v_mov_b32_e32 v106, v151
	v_mov_b32_e32 v101, v151
	v_mov_b32_e32 v100, v151
	v_mov_b32_e32 v99, v151
	v_mov_b32_e32 v98, v151
	v_mov_b32_e32 v93, v151
	v_mov_b32_e32 v92, v151
	v_mov_b32_e32 v91, v151
	v_mov_b32_e32 v90, v151
	v_mov_b32_e32 v85, v151
	v_mov_b32_e32 v84, v151
	v_mov_b32_e32 v83, v151
	v_mov_b32_e32 v82, v151
	v_mov_b32_e32 v81, v151
	v_mov_b32_e32 v80, v151
	v_mov_b32_e32 v79, v151
	v_mov_b32_e32 v78, v151
	v_mov_b32_e32 v73, v151
	v_mov_b32_e32 v72, v151
	v_mov_b32_e32 v71, v151
	v_mov_b32_e32 v70, v151
	v_mov_b32_e32 v65, v151
	v_mov_b32_e32 v64, v151
	v_mov_b32_e32 v63, v151
	v_mov_b32_e32 v62, v151
	v_mov_b32_e32 v57, v151
	v_mov_b32_e32 v56, v151
	v_mov_b32_e32 v55, v151
	v_mov_b32_e32 v54, v151
	v_mov_b32_e32 v49, v151
	v_mov_b32_e32 v48, v151
	v_mov_b32_e32 v47, v151
	v_mov_b32_e32 v46, v151
	v_mov_b32_e32 v41, v151
	v_mov_b32_e32 v40, v151
	v_mov_b32_e32 v39, v151
	v_mov_b32_e32 v38, v151
	v_mov_b32_e32 v33, v151
	v_mov_b32_e32 v32, v151
	v_mov_b32_e32 v31, v151
	v_mov_b32_e32 v30, v151
	v_mov_b32_e32 v25, v151
	v_mov_b32_e32 v24, v151
	v_mov_b32_e32 v23, v151
	v_mov_b32_e32 v22, v151
	v_mov_b32_e32 v77, v151
	v_mov_b32_e32 v76, v151
	v_mov_b32_e32 v75, v151
	v_mov_b32_e32 v74, v151
	v_mov_b32_e32 v69, v151
	v_mov_b32_e32 v68, v151
	v_mov_b32_e32 v67, v151
	v_mov_b32_e32 v66, v151
	v_mov_b32_e32 v61, v151
	v_mov_b32_e32 v60, v151
	v_mov_b32_e32 v59, v151
	v_mov_b32_e32 v58, v151
	v_mov_b32_e32 v53, v151
	v_mov_b32_e32 v52, v151
	v_mov_b32_e32 v51, v151
	v_mov_b32_e32 v50, v151
	v_mov_b32_e32 v45, v151
	v_mov_b32_e32 v44, v151
	v_mov_b32_e32 v43, v151
	v_mov_b32_e32 v42, v151
	v_mov_b32_e32 v37, v151
	v_mov_b32_e32 v36, v151
	v_mov_b32_e32 v35, v151
	v_mov_b32_e32 v34, v151
	v_mov_b32_e32 v29, v151
	v_mov_b32_e32 v28, v151
	v_mov_b32_e32 v27, v151
	v_mov_b32_e32 v26, v151
	v_mov_b32_e32 v21, v151
	v_mov_b32_e32 v20, v151
	v_mov_b32_e32 v19, v151
	v_mov_b32_e32 v18, v151
	s_branch .LBB0_1276

.LBB0_1345:
	s_ashr_i32 s5, s4, 31
	s_lshl_b64 s[10:11], s[4:5], 19
	v_readlane_b32 s12, v253, 46
	v_readlane_b32 s13, v253, 47
	s_add_u32 s10, s12, s10
	s_addc_u32 s11, s13, s11
	s_ashr_i32 s7, s6, 31
	s_lshl_b64 s[12:13], s[6:7], 19
	s_add_u32 s12, s20, s12
	s_addc_u32 s13, s21, s13
	s_andn2_b64 vcc, exec, s[0:1]
	s_cbranch_vccnz .Lzk_6
	s_and_b64 s[18:19], s[18:19], exec
	s_cselect_b32 s5, s11, s15
	s_cselect_b32 s7, s10, s14
	s_cselect_b32 s36, s13, s17
	s_cselect_b32 s37, s12, s16
	s_add_u32 s14, s14, 0x40080
	s_addc_u32 s15, s15, 0
	s_add_u32 s38, s16, 0x100
	v_mov_b32_e32 v18, 0
	v_mov_b32_e32 v218, 0xff800000
	v_mov_b32_e32 v214, 0xffffff80
	s_addc_u32 s39, s17, 0
	s_mov_b32 s16, 0
	v_mov_b32_e32 v19, v18
	v_mov_b32_e32 v20, v18
	v_mov_b32_e32 v21, v18
	v_mov_b32_e32 v22, v18
	v_mov_b32_e32 v23, v18
	v_mov_b32_e32 v24, v18
	v_mov_b32_e32 v25, v18
	v_mov_b32_e32 v34, v18
	v_mov_b32_e32 v35, v18
	v_mov_b32_e32 v36, v18
	v_mov_b32_e32 v37, v18
	v_mov_b32_e32 v38, v18
	v_mov_b32_e32 v39, v18
	v_mov_b32_e32 v40, v18
	v_mov_b32_e32 v41, v18
	v_mov_b32_e32 v50, v18
	v_mov_b32_e32 v51, v18
	v_mov_b32_e32 v52, v18
	v_mov_b32_e32 v53, v18
	v_mov_b32_e32 v54, v18
	v_mov_b32_e32 v55, v18
	v_mov_b32_e32 v56, v18
	v_mov_b32_e32 v57, v18
	v_mov_b32_e32 v66, v18
	v_mov_b32_e32 v67, v18
	v_mov_b32_e32 v68, v18
	v_mov_b32_e32 v69, v18
	v_mov_b32_e32 v70, v18
	v_mov_b32_e32 v71, v18
	v_mov_b32_e32 v72, v18
	v_mov_b32_e32 v73, v18
	v_mov_b32_e32 v26, v18
	v_mov_b32_e32 v27, v18
	v_mov_b32_e32 v28, v18
	v_mov_b32_e32 v29, v18
	v_mov_b32_e32 v30, v18
	v_mov_b32_e32 v31, v18
	v_mov_b32_e32 v32, v18
	v_mov_b32_e32 v33, v18
	v_mov_b32_e32 v42, v18
	v_mov_b32_e32 v43, v18
	v_mov_b32_e32 v44, v18
	v_mov_b32_e32 v45, v18
	v_mov_b32_e32 v46, v18
	v_mov_b32_e32 v47, v18
	v_mov_b32_e32 v48, v18
	v_mov_b32_e32 v49, v18
	v_mov_b32_e32 v58, v18
	v_mov_b32_e32 v59, v18
	v_mov_b32_e32 v60, v18
	v_mov_b32_e32 v61, v18
	v_mov_b32_e32 v62, v18
	v_mov_b32_e32 v63, v18
	v_mov_b32_e32 v64, v18
	v_mov_b32_e32 v65, v18
	v_mov_b32_e32 v74, v18
	v_mov_b32_e32 v75, v18
	v_mov_b32_e32 v76, v18
	v_mov_b32_e32 v77, v18
	v_mov_b32_e32 v78, v18
	v_mov_b32_e32 v79, v18
	v_mov_b32_e32 v80, v18
	v_mov_b32_e32 v81, v18
	v_mov_b32_e32 v82, v18
	v_mov_b32_e32 v83, v18
	v_mov_b32_e32 v84, v18
	v_mov_b32_e32 v85, v18
	v_mov_b32_e32 v86, v18
	v_mov_b32_e32 v87, v18
	v_mov_b32_e32 v88, v18
	v_mov_b32_e32 v89, v18
	v_mov_b32_e32 v98, v18
	v_mov_b32_e32 v99, v18
	v_mov_b32_e32 v100, v18
	v_mov_b32_e32 v101, v18
	v_mov_b32_e32 v102, v18
	v_mov_b32_e32 v103, v18
	v_mov_b32_e32 v104, v18
	v_mov_b32_e32 v105, v18
	v_mov_b32_e32 v114, v18
	v_mov_b32_e32 v115, v18
	v_mov_b32_e32 v116, v18
	v_mov_b32_e32 v117, v18
	v_mov_b32_e32 v118, v18
	v_mov_b32_e32 v119, v18
	v_mov_b32_e32 v120, v18
	v_mov_b32_e32 v121, v18
	v_mov_b32_e32 v130, v18
	v_mov_b32_e32 v131, v18
	v_mov_b32_e32 v132, v18
	v_mov_b32_e32 v133, v18
	v_mov_b32_e32 v134, v18
	v_mov_b32_e32 v135, v18
	v_mov_b32_e32 v136, v18
	v_mov_b32_e32 v137, v18
	v_mov_b32_e32 v90, v18
	v_mov_b32_e32 v91, v18
	v_mov_b32_e32 v92, v18
	v_mov_b32_e32 v93, v18
	v_mov_b32_e32 v94, v18
	v_mov_b32_e32 v95, v18
	v_mov_b32_e32 v96, v18
	v_mov_b32_e32 v97, v18
	v_mov_b32_e32 v106, v18
	v_mov_b32_e32 v107, v18
	v_mov_b32_e32 v108, v18
	v_mov_b32_e32 v109, v18
	v_mov_b32_e32 v110, v18
	v_mov_b32_e32 v111, v18
	v_mov_b32_e32 v112, v18
	v_mov_b32_e32 v113, v18
	v_mov_b32_e32 v122, v18
	v_mov_b32_e32 v123, v18
	v_mov_b32_e32 v124, v18
	v_mov_b32_e32 v125, v18
	v_mov_b32_e32 v126, v18
	v_mov_b32_e32 v127, v18
	v_mov_b32_e32 v128, v18
	v_mov_b32_e32 v129, v18
	v_mov_b32_e32 v148, v18
	v_mov_b32_e32 v149, v18
	v_mov_b32_e32 v150, v18
	v_mov_b32_e32 v151, v18
	v_mov_b32_e32 v138, v18
	v_mov_b32_e32 v139, v18
	v_mov_b32_e32 v140, v18
	v_mov_b32_e32 v141, v18
	s_mov_b64 s[46:47], 0x80

.Lzk_6:
	v_mov_b32_e32 v141, 0
	v_mov_b32_e32 v140, v141
	v_mov_b32_e32 v139, v141
	v_mov_b32_e32 v138, v141
	v_mov_b32_e32 v151, v141
	v_mov_b32_e32 v150, v141
	v_mov_b32_e32 v149, v141
	v_mov_b32_e32 v148, v141
	v_mov_b32_e32 v129, v141
	v_mov_b32_e32 v128, v141
	v_mov_b32_e32 v127, v141
	v_mov_b32_e32 v126, v141
	v_mov_b32_e32 v125, v141
	v_mov_b32_e32 v124, v141
	v_mov_b32_e32 v123, v141
	v_mov_b32_e32 v122, v141
	v_mov_b32_e32 v113, v141
	v_mov_b32_e32 v112, v141
	v_mov_b32_e32 v111, v141
	v_mov_b32_e32 v110, v141
	v_mov_b32_e32 v109, v141
	v_mov_b32_e32 v108, v141
	v_mov_b32_e32 v107, v141
	v_mov_b32_e32 v106, v141
	v_mov_b32_e32 v97, v141
	v_mov_b32_e32 v96, v141
	v_mov_b32_e32 v95, v141
	v_mov_b32_e32 v94, v141
	v_mov_b32_e32 v93, v141
	v_mov_b32_e32 v92, v141
	v_mov_b32_e32 v91, v141
	v_mov_b32_e32 v90, v141
	v_mov_b32_e32 v137, v141
	v_mov_b32_e32 v136, v141
	v_mov_b32_e32 v135, v141
	v_mov_b32_e32 v134, v141
	v_mov_b32_e32 v133, v141
	v_mov_b32_e32 v132, v141
	v_mov_b32_e32 v131, v141
	v_mov_b32_e32 v130, v141
	v_mov_b32_e32 v121, v141
	v_mov_b32_e32 v120, v141
	v_mov_b32_e32 v119, v141
	v_mov_b32_e32 v118, v141
	v_mov_b32_e32 v117, v141
	v_mov_b32_e32 v116, v141
	v_mov_b32_e32 v115, v141
	v_mov_b32_e32 v114, v141
	v_mov_b32_e32 v105, v141
	v_mov_b32_e32 v104, v141
	v_mov_b32_e32 v103, v141
	v_mov_b32_e32 v102, v141
	v_mov_b32_e32 v101, v141
	v_mov_b32_e32 v100, v141
	v_mov_b32_e32 v99, v141
	v_mov_b32_e32 v98, v141
	v_mov_b32_e32 v89, v141
	v_mov_b32_e32 v88, v141
	v_mov_b32_e32 v87, v141
	v_mov_b32_e32 v86, v141
	v_mov_b32_e32 v85, v141
	v_mov_b32_e32 v84, v141
	v_mov_b32_e32 v83, v141
	v_mov_b32_e32 v82, v141
	v_mov_b32_e32 v81, v141
	v_mov_b32_e32 v80, v141
	v_mov_b32_e32 v79, v141
	v_mov_b32_e32 v78, v141
	v_mov_b32_e32 v77, v141
	v_mov_b32_e32 v76, v141
	v_mov_b32_e32 v75, v141
	v_mov_b32_e32 v74, v141
	v_mov_b32_e32 v65, v141
	v_mov_b32_e32 v64, v141
	v_mov_b32_e32 v63, v141
	v_mov_b32_e32 v62, v141
	v_mov_b32_e32 v61, v141
	v_mov_b32_e32 v60, v141
	v_mov_b32_e32 v59, v141
	v_mov_b32_e32 v58, v141
	v_mov_b32_e32 v49, v141
	v_mov_b32_e32 v48, v141
	v_mov_b32_e32 v47, v141
	v_mov_b32_e32 v46, v141
	v_mov_b32_e32 v45, v141
	v_mov_b32_e32 v44, v141
	v_mov_b32_e32 v43, v141
	v_mov_b32_e32 v42, v141
	v_mov_b32_e32 v33, v141
	v_mov_b32_e32 v32, v141
	v_mov_b32_e32 v31, v141
	v_mov_b32_e32 v30, v141
	v_mov_b32_e32 v29, v141
	v_mov_b32_e32 v28, v141
	v_mov_b32_e32 v27, v141
	v_mov_b32_e32 v26, v141
	v_mov_b32_e32 v73, v141
	v_mov_b32_e32 v72, v141
	v_mov_b32_e32 v71, v141
	v_mov_b32_e32 v70, v141
	v_mov_b32_e32 v69, v141
	v_mov_b32_e32 v68, v141
	v_mov_b32_e32 v67, v141
	v_mov_b32_e32 v66, v141
	v_mov_b32_e32 v57, v141
	v_mov_b32_e32 v56, v141
	v_mov_b32_e32 v55, v141
	v_mov_b32_e32 v54, v141
	v_mov_b32_e32 v53, v141
	v_mov_b32_e32 v52, v141
	v_mov_b32_e32 v51, v141
	v_mov_b32_e32 v50, v141
	v_mov_b32_e32 v41, v141
	v_mov_b32_e32 v40, v141
	v_mov_b32_e32 v39, v141
	v_mov_b32_e32 v38, v141
	v_mov_b32_e32 v37, v141
	v_mov_b32_e32 v36, v141
	v_mov_b32_e32 v35, v141
	v_mov_b32_e32 v34, v141
	v_mov_b32_e32 v25, v141
	v_mov_b32_e32 v24, v141
	v_mov_b32_e32 v23, v141
	v_mov_b32_e32 v22, v141
	v_mov_b32_e32 v21, v141
	v_mov_b32_e32 v20, v141
	v_mov_b32_e32 v19, v141
	v_mov_b32_e32 v18, v141
	s_branch .LBB0_1342
